# all three GEMM phases (inproj, merge, outproj) hand-written: DMA pieces woven between MFMAs, epilogues staged through wave-private LDS and written as full 128-B row segments (dwordx4)
# speedup vs baseline: 1.1987x; 1.0336x over previous
; #define G_STORE(S, bf) { *(uint4*)&s->a[bf][srow][skc] = S##a0; *(uint4*)&s->a[bf][srow + 32][skc] = S##a1; \
;     if (MB == 2) { *(uint4*)&s->a[bf][srow + 64][skc] = S##a2; *(uint4*)&s->a[bf][srow + 96][skc] = S##a3; } \
;     *(uint4*)&s->b[bf][srow][skc] = S##b0; *(uint4*)&s->b[bf][srow + 32][skc] = S##b1; *(uint4*)&s->b[bf][srow + 64][skc] = S##b2; *(uint4*)&s->b[bf][srow + 96][skc] = S##b3; }
; template <int MB, bool PF2 = true>
; DI void gemm_main(const u16* __restrict__ A, int lda, const u16* __restrict__ B, int ldb, int K, f32x16 (&acc)[MB][2], GemmLds* s, int tid) {
;     ...
;   int KT = K >> 6;
;   asm volatile("" : "+s"(KT));
;   __syncthreads();
;   G_LOAD(p, 0); G_STORE(p, 0);
;   if (!PF2) {
;     __syncthreads();
;     for (int kt = 0; kt < KT; kt++) {
;       const int buf = kt & 1;
;       if (kt + 1 < KT) G_LOAD(p, (kt + 1) * 64);
;       if (buf) { G_COMPUTE(1); } else { G_COMPUTE(0); }
;       if (kt + 1 < KT) { if (buf) { G_STORE(p, 0); } else { G_STORE(p, 1); } }
;       __syncthreads();
;     }
;     return;
;   }
;   const int klast = K - 64;
;   G_LOAD(p, 64);
;   __syncthreads();
; DI void phase_inproj(const Params& p, int l, char* smem, int tid) {
;   const int lane = tid & 63, w = tid >> 6, r = lane & 31, h = lane >> 5, wm = w >> 1, wn = w & 1;
;   GemmLds* s = (GemmLds*)smem;
;   const u16* Wt = p.WtIn + (size_t)l * 3072 * 1024;
;   for (int it = blockIdx.x; it < 272 * 24; it += gridDim.x) {
;     const int mt = it / 24, nt = it % 24, m0 = mt * 128, n0 = nt * 128;
;     f32x16 acc[2][2]; zero_acc<2>(acc);
;     gemm_main<2>(p.xn + (size_t)m0 * 1024, 1024, Wt + (size_t)n0 * 1024, 1024, 1024, acc, s, tid);
.LBB0_515:
	v_readlane_b32 s0, v253, 14
	v_readlane_b32 s1, v253, 15
	v_mov_b32_e32 v0, v206
	s_andn2_b64 vcc, exec, s[0:1]
	s_cbranch_vccnz .LBB0_550
	v_readlane_b32 s0, v254, 19
	v_and_b32_e32 v113, 63, v206
	v_lshrrev_b32_e32 v114, 6, v206
	v_lshrrev_b32_e32 v115, 3, v113
	v_lshl_add_u32 v115, v114, 5, v115
	v_lshlrev_b32_e32 v115, 11, v115
	v_and_b32_e32 v116, 7, v113
	v_lshrrev_b32_e32 v113, 4, v113
	v_xor_b32_e32 v116, v116, v113
	v_lshl_or_b32 v98, v116, 4, v115
	v_xor_b32_e32 v99, 64, v98
	v_add_u32_e32 v99, 16384, v99
	v_add_u32_e32 v100, 32768, v98
	v_add_u32_e32 v101, 32768, v99
	v_lshrrev_b32_e32 v117, 6, v206
	v_and_b32_e32 v113, 31, v206
	v_bfe_u32 v114, v206, 5, 1
	v_bfe_u32 v115, v113, 1, 3
	v_xor_b32_e32 v115, v115, v114
	v_lshlrev_b32_e32 v115, 4, v115
	v_lshl_or_b32 v115, v113, 7, v115
	v_lshrrev_b32_e32 v116, 7, v206
	v_lshl_add_u32 v102, v116, 13, v115
	v_bfe_u32 v116, v206, 6, 1
	v_lshl_add_u32 v106, v116, 13, v115
	v_add_u32_e32 v106, 0x4000, v106
	v_xor_b32_e32 v103, 32, v102
	v_xor_b32_e32 v107, 32, v106
	v_xor_b32_e32 v104, 64, v102
	v_xor_b32_e32 v108, 64, v106
	v_xor_b32_e32 v105, 96, v102
	v_xor_b32_e32 v109, 96, v106
	v_and_b32_e32 v113, 31, v206
	v_lshrrev_b32_e32 v114, 7, v206
	v_lshl_add_u32 v113, v114, 6, v113
	v_bfe_u32 v115, v206, 5, 1
	v_lshlrev_b32_e32 v116, 3, v115
	v_mul_u32_u24_e32 v110, 0xe00, v113
	v_add_u32_e32 v110, v110, v116
	v_mul_u32_u24_e32 v111, 0x640, v113
	v_add_u32_e32 v111, v111, v116
	v_mul_u32_u24_e32 v116, 0x8800, v115
	v_lshl_add_u32 v112, v113, 1, v116
	v_lshrrev_b32_e32 v113, 6, v206
	v_mul_u32_u24_e32 v113, 0x2400, v113
	v_and_b32_e32 v114, 31, v206
	v_mul_u32_u24_e32 v114, 0x90, v114
	v_bfe_u32 v115, v206, 5, 1
	v_lshl_add_u32 v114, v115, 3, v114
	v_add_u32_e32 v118, v113, v114
	v_bfe_u32 v114, v206, 3, 3
	v_mul_u32_u24_e32 v114, 0x90, v114
	v_and_b32_e32 v115, 7, v206
	v_lshl_add_u32 v114, v115, 4, v114
	v_add_u32_e32 v119, v113, v114
	v_bfe_u32 v113, v206, 3, 3
	v_lshrrev_b32_e32 v114, 7, v206
	v_lshl_add_u32 v113, v114, 6, v113
	v_mul_u32_u24_e32 v113, 0xe00, v113
	v_bfe_u32 v114, v206, 6, 1
	v_lshlrev_b32_e32 v114, 7, v114
	v_and_b32_e32 v115, 7, v206
	v_lshl_or_b32 v114, v115, 4, v114
	v_add_u32_e32 v120, v113, v114
	v_bfe_u32 v113, v206, 3, 3
	v_lshrrev_b32_e32 v114, 7, v206
	v_lshl_add_u32 v113, v114, 6, v113
	v_mul_u32_u24_e32 v113, 0x640, v113
	v_bfe_u32 v114, v206, 6, 1
	v_lshlrev_b32_e32 v114, 7, v114
	v_and_b32_e32 v115, 7, v206
	v_lshl_or_b32 v114, v115, 4, v114
	v_add_u32_e32 v121, v113, v114
	v_readfirstlane_b32 s10, v117
	s_lshl_b32 s10, s10, 12
	s_mul_i32 s1, s0, 0x600000
	s_add_u32 s14, s96, 0x1ab20000
	s_addc_u32 s15, s97, 0
	s_add_u32 s14, s14, s1
	s_addc_u32 s15, s15, 0
	s_mov_b32 s12, s48
.Lip_item:
	s_cmpk_lt_u32 s12, 0x1980
	s_cbranch_scc0 .Lip_done
	s_barrier
	s_mul_hi_u32 s0, s12, 0xaaaaaaab
	s_lshr_b32 s0, s0, 4
	s_mul_i32 s1, s0, 24
	s_sub_u32 s1, s12, s1
	s_lshl_b32 s2, s0, 18
	s_add_u32 s4, s96, s2
	s_addc_u32 s5, s97, 0
	s_lshl_b32 s2, s1, 18
	s_add_u32 s8, s14, s2
	s_addc_u32 s9, s15, 0
	v_mov_b32_e32 v2, 0
	v_mov_b32_e32 v3, 0
	v_mov_b32_e32 v4, 0
	v_mov_b32_e32 v5, 0
	v_mov_b32_e32 v6, 0
	v_mov_b32_e32 v7, 0
	v_mov_b32_e32 v8, 0
	v_mov_b32_e32 v9, 0
	v_mov_b32_e32 v10, 0
	v_mov_b32_e32 v11, 0
	v_mov_b32_e32 v12, 0
	v_mov_b32_e32 v13, 0
	v_mov_b32_e32 v14, 0
	v_mov_b32_e32 v15, 0
	v_mov_b32_e32 v16, 0
	v_mov_b32_e32 v17, 0
	v_mov_b32_e32 v18, 0
	v_mov_b32_e32 v19, 0
	v_mov_b32_e32 v20, 0
	v_mov_b32_e32 v21, 0
	v_mov_b32_e32 v22, 0
	v_mov_b32_e32 v23, 0
	v_mov_b32_e32 v24, 0
	v_mov_b32_e32 v25, 0
	v_mov_b32_e32 v26, 0
	v_mov_b32_e32 v27, 0
	v_mov_b32_e32 v28, 0
	v_mov_b32_e32 v29, 0
	v_mov_b32_e32 v30, 0
	v_mov_b32_e32 v31, 0
	v_mov_b32_e32 v32, 0
	v_mov_b32_e32 v33, 0
	v_mov_b32_e32 v34, 0
	v_mov_b32_e32 v35, 0
	v_mov_b32_e32 v36, 0
	v_mov_b32_e32 v37, 0
	v_mov_b32_e32 v38, 0
	v_mov_b32_e32 v39, 0
	v_mov_b32_e32 v40, 0
	v_mov_b32_e32 v41, 0
	v_mov_b32_e32 v42, 0
	v_mov_b32_e32 v43, 0
	v_mov_b32_e32 v44, 0
	v_mov_b32_e32 v45, 0
	v_mov_b32_e32 v46, 0
	v_mov_b32_e32 v47, 0
	v_mov_b32_e32 v48, 0
	v_mov_b32_e32 v49, 0
	v_mov_b32_e32 v50, 0
	v_mov_b32_e32 v51, 0
	v_mov_b32_e32 v52, 0
	v_mov_b32_e32 v53, 0
	v_mov_b32_e32 v54, 0
	v_mov_b32_e32 v55, 0
	v_mov_b32_e32 v56, 0
	v_mov_b32_e32 v57, 0
	v_mov_b32_e32 v58, 0
	v_mov_b32_e32 v59, 0
	v_mov_b32_e32 v60, 0
	v_mov_b32_e32 v61, 0
	v_mov_b32_e32 v62, 0
	v_mov_b32_e32 v63, 0
	v_mov_b32_e32 v64, 0
	v_mov_b32_e32 v65, 0
	s_add_u32 m0, s10, 0x0
	s_nop 0
	global_load_lds_dwordx4 v98, s[4:5]
	s_add_u32 m0, s10, 0x400
	s_nop 0
	global_load_lds_dwordx4 v99, s[4:5]
	s_add_u32 m0, s10, 0x800
	s_nop 0
	global_load_lds_dwordx4 v100, s[4:5]
	s_add_u32 m0, s10, 0xc00
	s_nop 0
	global_load_lds_dwordx4 v101, s[4:5]
	s_add_u32 m0, s10, 0x4000
	s_nop 0
	global_load_lds_dwordx4 v98, s[8:9]
	s_add_u32 m0, s10, 0x4400
	s_nop 0
	global_load_lds_dwordx4 v99, s[8:9]
	s_add_u32 m0, s10, 0x4800
	s_nop 0
	global_load_lds_dwordx4 v100, s[8:9]
	s_add_u32 m0, s10, 0x4c00
	s_nop 0
	global_load_lds_dwordx4 v101, s[8:9]
	s_add_u32 s4, s4, 128
	s_addc_u32 s5, s5, 0
	s_add_u32 s8, s8, 128
	s_addc_u32 s9, s9, 0
	s_waitcnt vmcnt(0) lgkmcnt(0)
	s_barrier
	ds_read_b128 v[66:69], v102 offset:0
	ds_read_b128 v[74:77], v106 offset:0
	ds_read_b128 v[70:73], v102 offset:4096
	ds_read_b128 v[78:81], v106 offset:4096
	s_add_u32 m0, s10, 0x8000
	s_nop 0
	global_load_lds_dwordx4 v98, s[4:5]
	s_add_u32 m0, s10, 0x8400
	s_nop 0
	global_load_lds_dwordx4 v99, s[4:5]
	s_add_u32 m0, s10, 0x8800
	s_nop 0
	global_load_lds_dwordx4 v100, s[4:5]
	s_add_u32 m0, s10, 0x8c00
	s_nop 0
	global_load_lds_dwordx4 v101, s[4:5]
	s_add_u32 s4, s4, 128
	s_addc_u32 s5, s5, 0
	s_mov_b32 s11, 7
; #define G_STORE(S, bf) { *(uint4*)&s->a[bf][srow][skc] = S##a0; *(uint4*)&s->a[bf][srow + 32][skc] = S##a1; \
;     if (MB == 2) { *(uint4*)&s->a[bf][srow + 64][skc] = S##a2; *(uint4*)&s->a[bf][srow + 96][skc] = S##a3; } \
;     *(uint4*)&s->b[bf][srow][skc] = S##b0; *(uint4*)&s->b[bf][srow + 32][skc] = S##b1; *(uint4*)&s->b[bf][srow + 64][skc] = S##b2; *(uint4*)&s->b[bf][srow + 96][skc] = S##b3; }
; template <int MB, bool PF2 = true>
; DI void gemm_main(const u16* __restrict__ A, int lda, const u16* __restrict__ B, int ldb, int K, f32x16 (&acc)[MB][2], GemmLds* s, int tid) {
;     ...
;   for (int kt = 0; kt < KT; kt += 2) {
;     { const int k2 = min((kt + 2) * 64, klast); G_LOAD(q, k2); }
;     __builtin_amdgcn_sched_barrier(0);
;     G_COMPUTE(0);
;     G_STORE(p, 1);
;     __syncthreads();
;     { const int k3 = min((kt + 3) * 64, klast); G_LOAD(p, k3); }
;     __builtin_amdgcn_sched_barrier(0);
;     G_COMPUTE(1);
;     G_STORE(q, 0);
;     __syncthreads();
;   }
.Lip_loop:
	ds_read_b128 v[82:85], v103 offset:0
	ds_read_b128 v[90:93], v107 offset:0
	ds_read_b128 v[86:89], v103 offset:4096
	ds_read_b128 v[94:97], v107 offset:4096
	s_waitcnt lgkmcnt(4)
	s_add_u32 m0, s10, 0xc000
	v_mfma_f32_32x32x16_bf16 v[2:17], v[74:77], v[66:69], v[2:17]
	global_load_lds_dwordx4 v98, s[8:9]
	s_add_u32 m0, s10, 0xc400
	v_mfma_f32_32x32x16_bf16 v[18:33], v[78:81], v[66:69], v[18:33]
	global_load_lds_dwordx4 v99, s[8:9]
	s_add_u32 m0, s10, 0xc800
	v_mfma_f32_32x32x16_bf16 v[34:49], v[74:77], v[70:73], v[34:49]
	global_load_lds_dwordx4 v100, s[8:9]
	s_add_u32 m0, s10, 0xcc00
	v_mfma_f32_32x32x16_bf16 v[50:65], v[78:81], v[70:73], v[50:65]
	global_load_lds_dwordx4 v101, s[8:9]
	s_add_u32 s8, s8, 128
	s_addc_u32 s9, s9, 0
	ds_read_b128 v[66:69], v104 offset:0
	ds_read_b128 v[74:77], v108 offset:0
	ds_read_b128 v[70:73], v104 offset:4096
	ds_read_b128 v[78:81], v108 offset:4096
	s_waitcnt lgkmcnt(4)
	v_mfma_f32_32x32x16_bf16 v[2:17], v[90:93], v[82:85], v[2:17]
	v_mfma_f32_32x32x16_bf16 v[18:33], v[94:97], v[82:85], v[18:33]
	v_mfma_f32_32x32x16_bf16 v[34:49], v[90:93], v[86:89], v[34:49]
	v_mfma_f32_32x32x16_bf16 v[50:65], v[94:97], v[86:89], v[50:65]
	ds_read_b128 v[82:85], v105 offset:0
	ds_read_b128 v[90:93], v109 offset:0
	ds_read_b128 v[86:89], v105 offset:4096
	ds_read_b128 v[94:97], v109 offset:4096
	s_waitcnt lgkmcnt(4)
	v_mfma_f32_32x32x16_bf16 v[2:17], v[74:77], v[66:69], v[2:17]
	v_mfma_f32_32x32x16_bf16 v[18:33], v[78:81], v[66:69], v[18:33]
	v_mfma_f32_32x32x16_bf16 v[34:49], v[74:77], v[70:73], v[34:49]
	v_mfma_f32_32x32x16_bf16 v[50:65], v[78:81], v[70:73], v[50:65]
	s_waitcnt vmcnt(0) lgkmcnt(0)
	s_barrier
	ds_read_b128 v[66:69], v102 offset:32768
	ds_read_b128 v[74:77], v106 offset:32768
	ds_read_b128 v[70:73], v102 offset:36864
	ds_read_b128 v[78:81], v106 offset:36864
	s_cmp_eq_u32 s11, 0
	s_cbranch_scc1 .Lip_hold0
	s_add_u32 m0, s10, 0x0
	v_mfma_f32_32x32x16_bf16 v[2:17], v[90:93], v[82:85], v[2:17]
	global_load_lds_dwordx4 v98, s[4:5]
	s_add_u32 m0, s10, 0x400
	v_mfma_f32_32x32x16_bf16 v[18:33], v[94:97], v[82:85], v[18:33]
	global_load_lds_dwordx4 v99, s[4:5]
	s_add_u32 m0, s10, 0x800
	v_mfma_f32_32x32x16_bf16 v[34:49], v[90:93], v[86:89], v[34:49]
	global_load_lds_dwordx4 v100, s[4:5]
	s_add_u32 m0, s10, 0xc00
	v_mfma_f32_32x32x16_bf16 v[50:65], v[94:97], v[86:89], v[50:65]
	global_load_lds_dwordx4 v101, s[4:5]
	s_add_u32 s4, s4, 128
	s_addc_u32 s5, s5, 0
	s_branch .Lip_held0
.Lip_hold0:
	v_mfma_f32_32x32x16_bf16 v[2:17], v[90:93], v[82:85], v[2:17]
	v_mfma_f32_32x32x16_bf16 v[18:33], v[94:97], v[82:85], v[18:33]
	v_mfma_f32_32x32x16_bf16 v[34:49], v[90:93], v[86:89], v[34:49]
	v_mfma_f32_32x32x16_bf16 v[50:65], v[94:97], v[86:89], v[50:65]
.Lip_held0:
	s_cmp_eq_u32 s11, 0
	s_cbranch_scc1 .Lip_last
	ds_read_b128 v[82:85], v103 offset:32768
	ds_read_b128 v[90:93], v107 offset:32768
	ds_read_b128 v[86:89], v103 offset:36864
	ds_read_b128 v[94:97], v107 offset:36864
	s_waitcnt lgkmcnt(4)
	s_add_u32 m0, s10, 0x4000
	v_mfma_f32_32x32x16_bf16 v[2:17], v[74:77], v[66:69], v[2:17]
	global_load_lds_dwordx4 v98, s[8:9]
	s_add_u32 m0, s10, 0x4400
	v_mfma_f32_32x32x16_bf16 v[18:33], v[78:81], v[66:69], v[18:33]
	global_load_lds_dwordx4 v99, s[8:9]
	s_add_u32 m0, s10, 0x4800
	v_mfma_f32_32x32x16_bf16 v[34:49], v[74:77], v[70:73], v[34:49]
	global_load_lds_dwordx4 v100, s[8:9]
	s_add_u32 m0, s10, 0x4c00
	v_mfma_f32_32x32x16_bf16 v[50:65], v[78:81], v[70:73], v[50:65]
	global_load_lds_dwordx4 v101, s[8:9]
	s_add_u32 s8, s8, 128
	s_addc_u32 s9, s9, 0
	ds_read_b128 v[66:69], v104 offset:32768
	ds_read_b128 v[74:77], v108 offset:32768
	ds_read_b128 v[70:73], v104 offset:36864
	ds_read_b128 v[78:81], v108 offset:36864
	s_waitcnt lgkmcnt(4)
	v_mfma_f32_32x32x16_bf16 v[2:17], v[90:93], v[82:85], v[2:17]
	v_mfma_f32_32x32x16_bf16 v[18:33], v[94:97], v[82:85], v[18:33]
	v_mfma_f32_32x32x16_bf16 v[34:49], v[90:93], v[86:89], v[34:49]
	v_mfma_f32_32x32x16_bf16 v[50:65], v[94:97], v[86:89], v[50:65]
	ds_read_b128 v[82:85], v105 offset:32768
	ds_read_b128 v[90:93], v109 offset:32768
	ds_read_b128 v[86:89], v105 offset:36864
	ds_read_b128 v[94:97], v109 offset:36864
	s_waitcnt lgkmcnt(4)
	v_mfma_f32_32x32x16_bf16 v[2:17], v[74:77], v[66:69], v[2:17]
	v_mfma_f32_32x32x16_bf16 v[18:33], v[78:81], v[66:69], v[18:33]
	v_mfma_f32_32x32x16_bf16 v[34:49], v[74:77], v[70:73], v[34:49]
	v_mfma_f32_32x32x16_bf16 v[50:65], v[78:81], v[70:73], v[50:65]
	s_waitcnt vmcnt(0) lgkmcnt(0)
	s_barrier
	ds_read_b128 v[66:69], v102 offset:0
	ds_read_b128 v[74:77], v106 offset:0
	ds_read_b128 v[70:73], v102 offset:4096
	ds_read_b128 v[78:81], v106 offset:4096
	s_add_u32 m0, s10, 0x8000
	v_mfma_f32_32x32x16_bf16 v[2:17], v[90:93], v[82:85], v[2:17]
	global_load_lds_dwordx4 v98, s[4:5]
	s_add_u32 m0, s10, 0x8400
	v_mfma_f32_32x32x16_bf16 v[18:33], v[94:97], v[82:85], v[18:33]
	global_load_lds_dwordx4 v99, s[4:5]
	s_add_u32 m0, s10, 0x8800
	v_mfma_f32_32x32x16_bf16 v[34:49], v[90:93], v[86:89], v[34:49]
	global_load_lds_dwordx4 v100, s[4:5]
	s_add_u32 m0, s10, 0x8c00
	v_mfma_f32_32x32x16_bf16 v[50:65], v[94:97], v[86:89], v[50:65]
	global_load_lds_dwordx4 v101, s[4:5]
	s_add_u32 s4, s4, 128
	s_addc_u32 s5, s5, 0
	s_sub_u32 s11, s11, 1
	s_branch .Lip_loop
; DI u16 f2bf(float x) { return (u16)(pack2(x, 0.f) & 0xffffu); }
; DI int crow(int i, int h) { return (i & 3) + 8 * (i >> 2) + 4 * h; }
; DI void phase_inproj(const Params& p, int l, char* smem, int tid) {
;     ...
; #pragma unroll
;     for (int mb = 0; mb < 2; mb++)
; #pragma unroll
;       for (int nb = 0; nb < 2; nb++) {
;         const int rowb = m0 + wm * 64 + mb * 32, colb = n0 + wn * 64 + nb * 32, col = colb + r;
;         if (colb < 1792) {
;           const float qs = (colb < 256) ? 0.125f * LOG2E : 1.f;
; #pragma unroll
;           for (int i = 0; i < 16; i++) p.Pk[(size_t)(rowb + crow(i, h)) * PKW + col] = f2bf(acc[mb][nb][i] * qs);
.Lip_last:
	ds_read_b128 v[82:85], v103 offset:32768
	ds_read_b128 v[90:93], v107 offset:32768
	ds_read_b128 v[86:89], v103 offset:36864
	ds_read_b128 v[94:97], v107 offset:36864
	s_waitcnt lgkmcnt(4)
	v_mfma_f32_32x32x16_bf16 v[2:17], v[74:77], v[66:69], v[2:17]
	v_mfma_f32_32x32x16_bf16 v[18:33], v[78:81], v[66:69], v[18:33]
	v_mfma_f32_32x32x16_bf16 v[34:49], v[74:77], v[70:73], v[34:49]
	v_mfma_f32_32x32x16_bf16 v[50:65], v[78:81], v[70:73], v[50:65]
	ds_read_b128 v[66:69], v104 offset:32768
	ds_read_b128 v[74:77], v108 offset:32768
	ds_read_b128 v[70:73], v104 offset:36864
	ds_read_b128 v[78:81], v108 offset:36864
	s_waitcnt lgkmcnt(4)
	v_mfma_f32_32x32x16_bf16 v[2:17], v[90:93], v[82:85], v[2:17]
	v_mfma_f32_32x32x16_bf16 v[18:33], v[94:97], v[82:85], v[18:33]
	v_mfma_f32_32x32x16_bf16 v[34:49], v[90:93], v[86:89], v[34:49]
	v_mfma_f32_32x32x16_bf16 v[50:65], v[94:97], v[86:89], v[50:65]
	ds_read_b128 v[82:85], v105 offset:32768
	ds_read_b128 v[90:93], v109 offset:32768
	ds_read_b128 v[86:89], v105 offset:36864
	ds_read_b128 v[94:97], v109 offset:36864
	s_waitcnt lgkmcnt(4)
	v_mfma_f32_32x32x16_bf16 v[2:17], v[74:77], v[66:69], v[2:17]
	v_mfma_f32_32x32x16_bf16 v[18:33], v[78:81], v[66:69], v[18:33]
	v_mfma_f32_32x32x16_bf16 v[34:49], v[74:77], v[70:73], v[34:49]
	v_mfma_f32_32x32x16_bf16 v[50:65], v[78:81], v[70:73], v[50:65]
	s_waitcnt vmcnt(0) lgkmcnt(0)
	s_barrier
	v_mfma_f32_32x32x16_bf16 v[2:17], v[90:93], v[82:85], v[2:17]
	v_mfma_f32_32x32x16_bf16 v[18:33], v[94:97], v[82:85], v[18:33]
	v_mfma_f32_32x32x16_bf16 v[34:49], v[90:93], v[86:89], v[34:49]
	v_mfma_f32_32x32x16_bf16 v[50:65], v[94:97], v[86:89], v[50:65]
	s_nop 7
	s_nop 7
	s_bfe_u32 s2, s10, 0x1000c
	s_lshl_b32 s2, s2, 6
	s_lshl_b32 s16, s1, 7
	s_add_u32 s16, s16, s2
	s_cmpk_lt_u32 s16, 0x700
	s_cbranch_scc1 .Lip_rows_pk
	s_cmpk_lt_u32 s16, 0x9e1
	s_cbranch_scc1 .Lip_rows_pt
	s_branch .Lip_generic
.Lip_rows_pk:
	s_cmpk_lt_u32 s16, 0x100
	s_cbranch_scc0 .Lip_rows_pk_ns
	v_mul_f32_e32 v2, 0x3e38aa3b, v2
	v_mul_f32_e32 v3, 0x3e38aa3b, v3
	v_mul_f32_e32 v4, 0x3e38aa3b, v4
	v_mul_f32_e32 v5, 0x3e38aa3b, v5
	v_mul_f32_e32 v6, 0x3e38aa3b, v6
	v_mul_f32_e32 v7, 0x3e38aa3b, v7
	v_mul_f32_e32 v8, 0x3e38aa3b, v8
	v_mul_f32_e32 v9, 0x3e38aa3b, v9
	v_mul_f32_e32 v10, 0x3e38aa3b, v10
	v_mul_f32_e32 v11, 0x3e38aa3b, v11
	v_mul_f32_e32 v12, 0x3e38aa3b, v12
	v_mul_f32_e32 v13, 0x3e38aa3b, v13
	v_mul_f32_e32 v14, 0x3e38aa3b, v14
	v_mul_f32_e32 v15, 0x3e38aa3b, v15
	v_mul_f32_e32 v16, 0x3e38aa3b, v16
	v_mul_f32_e32 v17, 0x3e38aa3b, v17
	v_mul_f32_e32 v18, 0x3e38aa3b, v18
	v_mul_f32_e32 v19, 0x3e38aa3b, v19
	v_mul_f32_e32 v20, 0x3e38aa3b, v20
	v_mul_f32_e32 v21, 0x3e38aa3b, v21
	v_mul_f32_e32 v22, 0x3e38aa3b, v22
	v_mul_f32_e32 v23, 0x3e38aa3b, v23
	v_mul_f32_e32 v24, 0x3e38aa3b, v24
	v_mul_f32_e32 v25, 0x3e38aa3b, v25
	v_mul_f32_e32 v26, 0x3e38aa3b, v26
	v_mul_f32_e32 v27, 0x3e38aa3b, v27
	v_mul_f32_e32 v28, 0x3e38aa3b, v28
	v_mul_f32_e32 v29, 0x3e38aa3b, v29
	v_mul_f32_e32 v30, 0x3e38aa3b, v30
	v_mul_f32_e32 v31, 0x3e38aa3b, v31
	v_mul_f32_e32 v32, 0x3e38aa3b, v32
	v_mul_f32_e32 v33, 0x3e38aa3b, v33
	v_mul_f32_e32 v34, 0x3e38aa3b, v34
	v_mul_f32_e32 v35, 0x3e38aa3b, v35
	v_mul_f32_e32 v36, 0x3e38aa3b, v36
	v_mul_f32_e32 v37, 0x3e38aa3b, v37
	v_mul_f32_e32 v38, 0x3e38aa3b, v38
	v_mul_f32_e32 v39, 0x3e38aa3b, v39
	v_mul_f32_e32 v40, 0x3e38aa3b, v40
	v_mul_f32_e32 v41, 0x3e38aa3b, v41
	v_mul_f32_e32 v42, 0x3e38aa3b, v42
	v_mul_f32_e32 v43, 0x3e38aa3b, v43
	v_mul_f32_e32 v44, 0x3e38aa3b, v44
	v_mul_f32_e32 v45, 0x3e38aa3b, v45
	v_mul_f32_e32 v46, 0x3e38aa3b, v46
	v_mul_f32_e32 v47, 0x3e38aa3b, v47
	v_mul_f32_e32 v48, 0x3e38aa3b, v48
	v_mul_f32_e32 v49, 0x3e38aa3b, v49
	v_mul_f32_e32 v50, 0x3e38aa3b, v50
	v_mul_f32_e32 v51, 0x3e38aa3b, v51
	v_mul_f32_e32 v52, 0x3e38aa3b, v52
	v_mul_f32_e32 v53, 0x3e38aa3b, v53
	v_mul_f32_e32 v54, 0x3e38aa3b, v54
	v_mul_f32_e32 v55, 0x3e38aa3b, v55
	v_mul_f32_e32 v56, 0x3e38aa3b, v56
	v_mul_f32_e32 v57, 0x3e38aa3b, v57
	v_mul_f32_e32 v58, 0x3e38aa3b, v58
	v_mul_f32_e32 v59, 0x3e38aa3b, v59
	v_mul_f32_e32 v60, 0x3e38aa3b, v60
	v_mul_f32_e32 v61, 0x3e38aa3b, v61
	v_mul_f32_e32 v62, 0x3e38aa3b, v62
	v_mul_f32_e32 v63, 0x3e38aa3b, v63
	v_mul_f32_e32 v64, 0x3e38aa3b, v64
	v_mul_f32_e32 v65, 0x3e38aa3b, v65
; DI u16 f2bf(float x) { return (u16)(pack2(x, 0.f) & 0xffffu); }
; DI int crow(int i, int h) { return (i & 3) + 8 * (i >> 2) + 4 * h; }
; DI void phase_inproj(const Params& p, int l, char* smem, int tid) {
;     ...
; #pragma unroll
;     for (int mb = 0; mb < 2; mb++)
; #pragma unroll
;       for (int nb = 0; nb < 2; nb++) {
;         const int rowb = m0 + wm * 64 + mb * 32, colb = n0 + wn * 64 + nb * 32, col = colb + r;
;         if (colb < 1792) {
;           const float qs = (colb < 256) ? 0.125f * LOG2E : 1.f;
; #pragma unroll
;           for (int i = 0; i < 16; i++) p.Pk[(size_t)(rowb + crow(i, h)) * PKW + col] = f2bf(acc[mb][nb][i] * qs);
;         } else if (colb < 2592) {
; #pragma unroll
;           for (int i = 0; i < 16; i++) p.Pt[(size_t)(rowb + crow(i, h)) * PTW + col - 1792] = f2bf(acc[mb][nb][i]);
.Lip_rows_pk_ns:
	s_mul_i32 s2, s0, 0x70000
	s_lshl_b32 s3, s1, 8
	s_add_u32 s2, s2, s3
	s_add_u32 s2, s2, 0x4400000
	s_add_u32 s6, s96, s2
	s_addc_u32 s7, s97, 0
	v_cvt_pk_bf16_f32 v66, v2, v3
	v_cvt_pk_bf16_f32 v67, v4, v5
	ds_write_b64 v118, v[66:67] offset:0
	v_cvt_pk_bf16_f32 v68, v6, v7
	v_cvt_pk_bf16_f32 v69, v8, v9
	ds_write_b64 v118, v[68:69] offset:16
	v_cvt_pk_bf16_f32 v70, v10, v11
	v_cvt_pk_bf16_f32 v71, v12, v13
	ds_write_b64 v118, v[70:71] offset:32
	v_cvt_pk_bf16_f32 v72, v14, v15
	v_cvt_pk_bf16_f32 v73, v16, v17
	ds_write_b64 v118, v[72:73] offset:48
	v_cvt_pk_bf16_f32 v66, v18, v19
	v_cvt_pk_bf16_f32 v67, v20, v21
	ds_write_b64 v118, v[66:67] offset:64
	v_cvt_pk_bf16_f32 v68, v22, v23
	v_cvt_pk_bf16_f32 v69, v24, v25
	ds_write_b64 v118, v[68:69] offset:80
	v_cvt_pk_bf16_f32 v70, v26, v27
	v_cvt_pk_bf16_f32 v71, v28, v29
	ds_write_b64 v118, v[70:71] offset:96
	v_cvt_pk_bf16_f32 v72, v30, v31
	v_cvt_pk_bf16_f32 v73, v32, v33
	ds_write_b64 v118, v[72:73] offset:112
	v_cvt_pk_bf16_f32 v66, v34, v35
	v_cvt_pk_bf16_f32 v67, v36, v37
	ds_write_b64 v118, v[66:67] offset:4608
	v_cvt_pk_bf16_f32 v68, v38, v39
	v_cvt_pk_bf16_f32 v69, v40, v41
	ds_write_b64 v118, v[68:69] offset:4624
	v_cvt_pk_bf16_f32 v70, v42, v43
	v_cvt_pk_bf16_f32 v71, v44, v45
	ds_write_b64 v118, v[70:71] offset:4640
	v_cvt_pk_bf16_f32 v72, v46, v47
	v_cvt_pk_bf16_f32 v73, v48, v49
	ds_write_b64 v118, v[72:73] offset:4656
	v_cvt_pk_bf16_f32 v66, v50, v51
	v_cvt_pk_bf16_f32 v67, v52, v53
	ds_write_b64 v118, v[66:67] offset:4672
	v_cvt_pk_bf16_f32 v68, v54, v55
	v_cvt_pk_bf16_f32 v69, v56, v57
	ds_write_b64 v118, v[68:69] offset:4688
	v_cvt_pk_bf16_f32 v70, v58, v59
	v_cvt_pk_bf16_f32 v71, v60, v61
	ds_write_b64 v118, v[70:71] offset:4704
	v_cvt_pk_bf16_f32 v72, v62, v63
	v_cvt_pk_bf16_f32 v73, v64, v65
	ds_write_b64 v118, v[72:73] offset:4720
	ds_read_b128 v[74:77], v119 offset:0
	ds_read_b128 v[78:81], v119 offset:1152
	ds_read_b128 v[82:85], v119 offset:2304
	ds_read_b128 v[86:89], v119 offset:3456
	ds_read_b128 v[90:93], v119 offset:4608
	ds_read_b128 v[94:97], v119 offset:5760
	ds_read_b128 v[122:125], v119 offset:6912
	ds_read_b128 v[126:129], v119 offset:8064
	s_waitcnt lgkmcnt(7)
	global_store_dwordx4 v120, v[74:77], s[6:7]
	s_add_u32 s6, s6, 0x7000
	s_addc_u32 s7, s7, 0
	s_waitcnt lgkmcnt(6)
	global_store_dwordx4 v120, v[78:81], s[6:7]
	s_add_u32 s6, s6, 0x7000
	s_addc_u32 s7, s7, 0
	s_waitcnt lgkmcnt(5)
	global_store_dwordx4 v120, v[82:85], s[6:7]
	s_add_u32 s6, s6, 0x7000
	s_addc_u32 s7, s7, 0
	s_waitcnt lgkmcnt(4)
	global_store_dwordx4 v120, v[86:89], s[6:7]
	s_add_u32 s6, s6, 0x7000
	s_addc_u32 s7, s7, 0
	s_waitcnt lgkmcnt(3)
	global_store_dwordx4 v120, v[90:93], s[6:7]
	s_add_u32 s6, s6, 0x7000
	s_addc_u32 s7, s7, 0
	s_waitcnt lgkmcnt(2)
	global_store_dwordx4 v120, v[94:97], s[6:7]
	s_add_u32 s6, s6, 0x7000
	s_addc_u32 s7, s7, 0
	s_waitcnt lgkmcnt(1)
	global_store_dwordx4 v120, v[122:125], s[6:7]
	s_add_u32 s6, s6, 0x7000
	s_addc_u32 s7, s7, 0
	s_waitcnt lgkmcnt(0)
	global_store_dwordx4 v120, v[126:129], s[6:7]
	s_branch .Lip_epi_done
.Lip_rows_pt:
	s_mul_i32 s2, s0, 0x32000
	s_lshl_b32 s3, s1, 8
	s_sub_u32 s3, s3, 0xe00
	s_add_u32 s2, s2, s3
	s_add_u32 s2, s2, 0xbb00000
	s_add_u32 s6, s96, s2
	s_addc_u32 s7, s97, 0
	v_cvt_pk_bf16_f32 v66, v2, v3
	v_cvt_pk_bf16_f32 v67, v4, v5
	ds_write_b64 v118, v[66:67] offset:0
	v_cvt_pk_bf16_f32 v68, v6, v7
	v_cvt_pk_bf16_f32 v69, v8, v9
	ds_write_b64 v118, v[68:69] offset:16
	v_cvt_pk_bf16_f32 v70, v10, v11
	v_cvt_pk_bf16_f32 v71, v12, v13
	ds_write_b64 v118, v[70:71] offset:32
	v_cvt_pk_bf16_f32 v72, v14, v15
	v_cvt_pk_bf16_f32 v73, v16, v17
	ds_write_b64 v118, v[72:73] offset:48
	v_cvt_pk_bf16_f32 v66, v18, v19
	v_cvt_pk_bf16_f32 v67, v20, v21
	ds_write_b64 v118, v[66:67] offset:64
	v_cvt_pk_bf16_f32 v68, v22, v23
	v_cvt_pk_bf16_f32 v69, v24, v25
	ds_write_b64 v118, v[68:69] offset:80
	v_cvt_pk_bf16_f32 v70, v26, v27
	v_cvt_pk_bf16_f32 v71, v28, v29
	ds_write_b64 v118, v[70:71] offset:96
	v_cvt_pk_bf16_f32 v72, v30, v31
	v_cvt_pk_bf16_f32 v73, v32, v33
	ds_write_b64 v118, v[72:73] offset:112
	v_cvt_pk_bf16_f32 v66, v34, v35
	v_cvt_pk_bf16_f32 v67, v36, v37
	ds_write_b64 v118, v[66:67] offset:4608
	v_cvt_pk_bf16_f32 v68, v38, v39
	v_cvt_pk_bf16_f32 v69, v40, v41
	ds_write_b64 v118, v[68:69] offset:4624
	v_cvt_pk_bf16_f32 v70, v42, v43
	v_cvt_pk_bf16_f32 v71, v44, v45
	ds_write_b64 v118, v[70:71] offset:4640
	v_cvt_pk_bf16_f32 v72, v46, v47
	v_cvt_pk_bf16_f32 v73, v48, v49
	ds_write_b64 v118, v[72:73] offset:4656
	v_cvt_pk_bf16_f32 v66, v50, v51
	v_cvt_pk_bf16_f32 v67, v52, v53
	ds_write_b64 v118, v[66:67] offset:4672
	v_cvt_pk_bf16_f32 v68, v54, v55
	v_cvt_pk_bf16_f32 v69, v56, v57
	ds_write_b64 v118, v[68:69] offset:4688
	v_cvt_pk_bf16_f32 v70, v58, v59
	v_cvt_pk_bf16_f32 v71, v60, v61
	ds_write_b64 v118, v[70:71] offset:4704
	v_cvt_pk_bf16_f32 v72, v62, v63
	v_cvt_pk_bf16_f32 v73, v64, v65
	ds_write_b64 v118, v[72:73] offset:4720
	ds_read_b128 v[74:77], v119 offset:0
	ds_read_b128 v[78:81], v119 offset:1152
	ds_read_b128 v[82:85], v119 offset:2304
	ds_read_b128 v[86:89], v119 offset:3456
	ds_read_b128 v[90:93], v119 offset:4608
	ds_read_b128 v[94:97], v119 offset:5760
	ds_read_b128 v[122:125], v119 offset:6912
	ds_read_b128 v[126:129], v119 offset:8064
	s_waitcnt lgkmcnt(7)
	global_store_dwordx4 v121, v[74:77], s[6:7]
	s_add_u32 s6, s6, 0x3200
	s_addc_u32 s7, s7, 0
	s_waitcnt lgkmcnt(6)
	global_store_dwordx4 v121, v[78:81], s[6:7]
	s_add_u32 s6, s6, 0x3200
	s_addc_u32 s7, s7, 0
	s_waitcnt lgkmcnt(5)
	global_store_dwordx4 v121, v[82:85], s[6:7]
	s_add_u32 s6, s6, 0x3200
	s_addc_u32 s7, s7, 0
	s_waitcnt lgkmcnt(4)
	global_store_dwordx4 v121, v[86:89], s[6:7]
	s_add_u32 s6, s6, 0x3200
	s_addc_u32 s7, s7, 0
	s_waitcnt lgkmcnt(3)
	global_store_dwordx4 v121, v[90:93], s[6:7]
	s_add_u32 s6, s6, 0x3200
	s_addc_u32 s7, s7, 0
	s_waitcnt lgkmcnt(2)
	global_store_dwordx4 v121, v[94:97], s[6:7]
	s_add_u32 s6, s6, 0x3200
	s_addc_u32 s7, s7, 0
	s_waitcnt lgkmcnt(1)
	global_store_dwordx4 v121, v[122:125], s[6:7]
	s_add_u32 s6, s6, 0x3200
	s_addc_u32 s7, s7, 0
	s_waitcnt lgkmcnt(0)
	global_store_dwordx4 v121, v[126:129], s[6:7]
	s_branch .Lip_epi_done
; DI u16 f2bf(float x) { return (u16)(pack2(x, 0.f) & 0xffffu); }
; DI int crow(int i, int h) { return (i & 3) + 8 * (i >> 2) + 4 * h; }
; DI void phase_inproj(const Params& p, int l, char* smem, int tid) {
;     ...
; #pragma unroll
;     for (int mb = 0; mb < 2; mb++)
; #pragma unroll
;       for (int nb = 0; nb < 2; nb++) {
;         const int rowb = m0 + wm * 64 + mb * 32, colb = n0 + wn * 64 + nb * 32, col = colb + r;
;         if (colb < 1792) {
;           const float qs = (colb < 256) ? 0.125f * LOG2E : 1.f;
; #pragma unroll
;           for (int i = 0; i < 16; i++) p.Pk[(size_t)(rowb + crow(i, h)) * PKW + col] = f2bf(acc[mb][nb][i] * qs);
;         } else if (colb < 2592) {
; #pragma unroll
;           for (int i = 0; i < 16; i++) p.Pt[(size_t)(rowb + crow(i, h)) * PTW + col - 1792] = f2bf(acc[mb][nb][i]);
;         }
;       }
; #pragma unroll
;     for (int nb = 0; nb < 2; nb++) {
;       const int colb = n0 + wn * 64 + nb * 32;
;       if (colb >= 2592 && colb < 2976) {
;         const int rw = m0 + wm * 64;
;         float v[2][16];
; #pragma unroll
;         for (int mb = 0; mb < 2; mb++)
; #pragma unroll
;           for (int i = 0; i < 16; i++) v[mb][i] = acc[mb][nb][i];
;         vt_store32(v, (u16*)smem + w * (32 * 72), p.VtAD + ((size_t)(rw / SEQA) * 384 + colb - 2592) * SEQA + rw % SEQA, lane);
;       }
;     }
.Lip_generic:
	s_bfe_u32 s2, s10, 0x1000c
	s_lshl_b32 s2, s2, 6
	s_lshl_b32 s16, s1, 7
	s_add_u32 s16, s16, s2
	s_cmpk_lt_u32 s16, 0x700
	s_cbranch_scc1 .Lip_e0_pk
	s_cmpk_lt_u32 s16, 0xa20
	s_cbranch_scc1 .Lip_e0_pt
	s_cmpk_lt_u32 s16, 0xba0
	s_cbranch_scc1 .Lip_e0_vt
	s_branch .Lip_e0_end
.Lip_e0_pk:
	s_mul_i32 s2, s0, 0x70000
	s_lshl_b32 s3, s16, 1
	s_add_u32 s2, s2, s3
	s_add_u32 s2, s2, 0x4400000
	s_add_u32 s6, s96, s2
	s_addc_u32 s7, s97, 0
	s_add_u32 s2, s6, 0x1c000
	s_addc_u32 s3, s7, 0
	s_cmpk_lt_u32 s16, 0x100
	s_cbranch_scc0 .Lip_e0_pk_noscale
	v_mul_f32_e32 v2, 0x3e38aa3b, v2
	v_mul_f32_e32 v3, 0x3e38aa3b, v3
	v_mul_f32_e32 v4, 0x3e38aa3b, v4
	v_mul_f32_e32 v5, 0x3e38aa3b, v5
	v_mul_f32_e32 v6, 0x3e38aa3b, v6
	v_mul_f32_e32 v7, 0x3e38aa3b, v7
	v_mul_f32_e32 v8, 0x3e38aa3b, v8
	v_mul_f32_e32 v9, 0x3e38aa3b, v9
	v_mul_f32_e32 v10, 0x3e38aa3b, v10
	v_mul_f32_e32 v11, 0x3e38aa3b, v11
	v_mul_f32_e32 v12, 0x3e38aa3b, v12
	v_mul_f32_e32 v13, 0x3e38aa3b, v13
	v_mul_f32_e32 v14, 0x3e38aa3b, v14
	v_mul_f32_e32 v15, 0x3e38aa3b, v15
	v_mul_f32_e32 v16, 0x3e38aa3b, v16
	v_mul_f32_e32 v17, 0x3e38aa3b, v17
	v_mul_f32_e32 v34, 0x3e38aa3b, v34
	v_mul_f32_e32 v35, 0x3e38aa3b, v35
	v_mul_f32_e32 v36, 0x3e38aa3b, v36
	v_mul_f32_e32 v37, 0x3e38aa3b, v37
	v_mul_f32_e32 v38, 0x3e38aa3b, v38
	v_mul_f32_e32 v39, 0x3e38aa3b, v39
	v_mul_f32_e32 v40, 0x3e38aa3b, v40
	v_mul_f32_e32 v41, 0x3e38aa3b, v41
	v_mul_f32_e32 v42, 0x3e38aa3b, v42
	v_mul_f32_e32 v43, 0x3e38aa3b, v43
	v_mul_f32_e32 v44, 0x3e38aa3b, v44
	v_mul_f32_e32 v45, 0x3e38aa3b, v45
	v_mul_f32_e32 v46, 0x3e38aa3b, v46
	v_mul_f32_e32 v47, 0x3e38aa3b, v47
	v_mul_f32_e32 v48, 0x3e38aa3b, v48
	v_mul_f32_e32 v49, 0x3e38aa3b, v49
.Lip_e0_pk_noscale:
	v_cvt_pk_bf16_f32 v66, v2, v3
	v_cvt_pk_bf16_f32 v67, v4, v5
	global_store_dwordx2 v110, v[66:67], s[6:7] offset:0
	v_cvt_pk_bf16_f32 v68, v6, v7
	v_cvt_pk_bf16_f32 v69, v8, v9
	global_store_dwordx2 v110, v[68:69], s[6:7] offset:16
	v_cvt_pk_bf16_f32 v70, v10, v11
	v_cvt_pk_bf16_f32 v71, v12, v13
	global_store_dwordx2 v110, v[70:71], s[6:7] offset:32
	v_cvt_pk_bf16_f32 v72, v14, v15
	v_cvt_pk_bf16_f32 v73, v16, v17
	global_store_dwordx2 v110, v[72:73], s[6:7] offset:48
	v_cvt_pk_bf16_f32 v66, v34, v35
	v_cvt_pk_bf16_f32 v67, v36, v37
	global_store_dwordx2 v110, v[66:67], s[2:3] offset:0
	v_cvt_pk_bf16_f32 v68, v38, v39
	v_cvt_pk_bf16_f32 v69, v40, v41
	global_store_dwordx2 v110, v[68:69], s[2:3] offset:16
	v_cvt_pk_bf16_f32 v70, v42, v43
	v_cvt_pk_bf16_f32 v71, v44, v45
	global_store_dwordx2 v110, v[70:71], s[2:3] offset:32
	v_cvt_pk_bf16_f32 v72, v46, v47
	v_cvt_pk_bf16_f32 v73, v48, v49
	global_store_dwordx2 v110, v[72:73], s[2:3] offset:48
	s_branch .Lip_e0_end
.Lip_e0_pt:
	s_mul_i32 s2, s0, 0x32000
	s_sub_u32 s3, s16, 0x700
	s_lshl_b32 s3, s3, 1
	s_add_u32 s2, s2, s3
	s_add_u32 s2, s2, 0xbb00000
	s_add_u32 s6, s96, s2
	s_addc_u32 s7, s97, 0
	s_add_u32 s2, s6, 0xc800
	s_addc_u32 s3, s7, 0
	v_cvt_pk_bf16_f32 v66, v2, v3
	v_cvt_pk_bf16_f32 v67, v4, v5
	global_store_dwordx2 v111, v[66:67], s[6:7] offset:0
	v_cvt_pk_bf16_f32 v68, v6, v7
	v_cvt_pk_bf16_f32 v69, v8, v9
	global_store_dwordx2 v111, v[68:69], s[6:7] offset:16
	v_cvt_pk_bf16_f32 v70, v10, v11
	v_cvt_pk_bf16_f32 v71, v12, v13
	global_store_dwordx2 v111, v[70:71], s[6:7] offset:32
	v_cvt_pk_bf16_f32 v72, v14, v15
	v_cvt_pk_bf16_f32 v73, v16, v17
	global_store_dwordx2 v111, v[72:73], s[6:7] offset:48
	v_cvt_pk_bf16_f32 v66, v34, v35
	v_cvt_pk_bf16_f32 v67, v36, v37
	global_store_dwordx2 v111, v[66:67], s[2:3] offset:0
	v_cvt_pk_bf16_f32 v68, v38, v39
	v_cvt_pk_bf16_f32 v69, v40, v41
	global_store_dwordx2 v111, v[68:69], s[2:3] offset:16
	v_cvt_pk_bf16_f32 v70, v42, v43
	v_cvt_pk_bf16_f32 v71, v44, v45
	global_store_dwordx2 v111, v[70:71], s[2:3] offset:32
	v_cvt_pk_bf16_f32 v72, v46, v47
	v_cvt_pk_bf16_f32 v73, v48, v49
	global_store_dwordx2 v111, v[72:73], s[2:3] offset:48
	s_branch .Lip_e0_end
.Lip_e0_vt:
	s_mul_hi_u32 s2, s0, 0x78787879
	s_lshr_b32 s2, s2, 4
	s_mul_i32 s3, s2, 34
	s_sub_u32 s3, s0, s3
	s_lshl_b32 s3, s3, 8
	s_mul_i32 s2, s2, 0x330000
	s_add_u32 s2, s2, s3
	s_sub_u32 s3, s16, 0xa20
	s_mul_i32 s3, s3, 0x2200
	s_add_u32 s2, s2, s3
	s_add_u32 s2, s2, 0xf020000
	s_add_u32 s6, s96, s2
	s_addc_u32 s7, s97, 0
	v_add_u32_e32 v74, 0x0, v112
	v_cvt_pk_bf16_f32 v66, v2, v2
	global_store_short v74, v66, s[6:7]
	v_add_u32_e32 v75, 0x2200, v112
	v_cvt_pk_bf16_f32 v68, v3, v3
	global_store_short v75, v68, s[6:7]
	v_add_u32_e32 v76, 0x4400, v112
	v_cvt_pk_bf16_f32 v70, v4, v4
	global_store_short v76, v70, s[6:7]
	v_add_u32_e32 v77, 0x6600, v112
	v_cvt_pk_bf16_f32 v72, v5, v5
	global_store_short v77, v72, s[6:7]
	v_add_u32_e32 v74, 0x11000, v112
	v_cvt_pk_bf16_f32 v66, v6, v6
	global_store_short v74, v66, s[6:7]
	v_add_u32_e32 v75, 0x13200, v112
	v_cvt_pk_bf16_f32 v68, v7, v7
	global_store_short v75, v68, s[6:7]
	v_add_u32_e32 v76, 0x15400, v112
	v_cvt_pk_bf16_f32 v70, v8, v8
	global_store_short v76, v70, s[6:7]
	v_add_u32_e32 v77, 0x17600, v112
	v_cvt_pk_bf16_f32 v72, v9, v9
	global_store_short v77, v72, s[6:7]
	v_add_u32_e32 v74, 0x22000, v112
	v_cvt_pk_bf16_f32 v66, v10, v10
	global_store_short v74, v66, s[6:7]
	v_add_u32_e32 v75, 0x24200, v112
	v_cvt_pk_bf16_f32 v68, v11, v11
	global_store_short v75, v68, s[6:7]
	v_add_u32_e32 v76, 0x26400, v112
	v_cvt_pk_bf16_f32 v70, v12, v12
	global_store_short v76, v70, s[6:7]
	v_add_u32_e32 v77, 0x28600, v112
	v_cvt_pk_bf16_f32 v72, v13, v13
	global_store_short v77, v72, s[6:7]
	v_add_u32_e32 v74, 0x33000, v112
	v_cvt_pk_bf16_f32 v66, v14, v14
	global_store_short v74, v66, s[6:7]
	v_add_u32_e32 v75, 0x35200, v112
	v_cvt_pk_bf16_f32 v68, v15, v15
; DI u16 f2bf(float x) { return (u16)(pack2(x, 0.f) & 0xffffu); }
; DI int crow(int i, int h) { return (i & 3) + 8 * (i >> 2) + 4 * h; }
; DI void phase_inproj(const Params& p, int l, char* smem, int tid) {
;     ...
; #pragma unroll
;     for (int mb = 0; mb < 2; mb++)
; #pragma unroll
;       for (int nb = 0; nb < 2; nb++) {
;         const int rowb = m0 + wm * 64 + mb * 32, colb = n0 + wn * 64 + nb * 32, col = colb + r;
;         if (colb < 1792) {
;           const float qs = (colb < 256) ? 0.125f * LOG2E : 1.f;
; #pragma unroll
;           for (int i = 0; i < 16; i++) p.Pk[(size_t)(rowb + crow(i, h)) * PKW + col] = f2bf(acc[mb][nb][i] * qs);
;         } else if (colb < 2592) {
; #pragma unroll
;           for (int i = 0; i < 16; i++) p.Pt[(size_t)(rowb + crow(i, h)) * PTW + col - 1792] = f2bf(acc[mb][nb][i]);
;         }
;       }
; #pragma unroll
;     for (int nb = 0; nb < 2; nb++) {
;       const int colb = n0 + wn * 64 + nb * 32;
;       if (colb >= 2592 && colb < 2976) {
;         const int rw = m0 + wm * 64;
;         float v[2][16];
; #pragma unroll
;         for (int mb = 0; mb < 2; mb++)
; #pragma unroll
;           for (int i = 0; i < 16; i++) v[mb][i] = acc[mb][nb][i];
;         vt_store32(v, (u16*)smem + w * (32 * 72), p.VtAD + ((size_t)(rw / SEQA) * 384 + colb - 2592) * SEQA + rw % SEQA, lane);
;       }
;     }
	global_store_short v75, v68, s[6:7]
	v_add_u32_e32 v76, 0x37400, v112
	v_cvt_pk_bf16_f32 v70, v16, v16
	global_store_short v76, v70, s[6:7]
	v_add_u32_e32 v77, 0x39600, v112
	v_cvt_pk_bf16_f32 v72, v17, v17
	global_store_short v77, v72, s[6:7]
	v_add_u32_e32 v74, 0x40, v112
	v_cvt_pk_bf16_f32 v66, v34, v34
	global_store_short v74, v66, s[6:7]
	v_add_u32_e32 v75, 0x2240, v112
	v_cvt_pk_bf16_f32 v68, v35, v35
	global_store_short v75, v68, s[6:7]
	v_add_u32_e32 v76, 0x4440, v112
	v_cvt_pk_bf16_f32 v70, v36, v36
	global_store_short v76, v70, s[6:7]
	v_add_u32_e32 v77, 0x6640, v112
	v_cvt_pk_bf16_f32 v72, v37, v37
	global_store_short v77, v72, s[6:7]
	v_add_u32_e32 v74, 0x11040, v112
	v_cvt_pk_bf16_f32 v66, v38, v38
	global_store_short v74, v66, s[6:7]
	v_add_u32_e32 v75, 0x13240, v112
	v_cvt_pk_bf16_f32 v68, v39, v39
	global_store_short v75, v68, s[6:7]
	v_add_u32_e32 v76, 0x15440, v112
	v_cvt_pk_bf16_f32 v70, v40, v40
	global_store_short v76, v70, s[6:7]
	v_add_u32_e32 v77, 0x17640, v112
	v_cvt_pk_bf16_f32 v72, v41, v41
	global_store_short v77, v72, s[6:7]
	v_add_u32_e32 v74, 0x22040, v112
	v_cvt_pk_bf16_f32 v66, v42, v42
	global_store_short v74, v66, s[6:7]
	v_add_u32_e32 v75, 0x24240, v112
	v_cvt_pk_bf16_f32 v68, v43, v43
	global_store_short v75, v68, s[6:7]
	v_add_u32_e32 v76, 0x26440, v112
	v_cvt_pk_bf16_f32 v70, v44, v44
	global_store_short v76, v70, s[6:7]
	v_add_u32_e32 v77, 0x28640, v112
	v_cvt_pk_bf16_f32 v72, v45, v45
	global_store_short v77, v72, s[6:7]
	v_add_u32_e32 v74, 0x33040, v112
	v_cvt_pk_bf16_f32 v66, v46, v46
	global_store_short v74, v66, s[6:7]
	v_add_u32_e32 v75, 0x35240, v112
	v_cvt_pk_bf16_f32 v68, v47, v47
	global_store_short v75, v68, s[6:7]
	v_add_u32_e32 v76, 0x37440, v112
	v_cvt_pk_bf16_f32 v70, v48, v48
	global_store_short v76, v70, s[6:7]
	v_add_u32_e32 v77, 0x39640, v112
	v_cvt_pk_bf16_f32 v72, v49, v49
	global_store_short v77, v72, s[6:7]
.Lip_e0_end:
	s_bfe_u32 s2, s10, 0x1000c
	s_lshl_b32 s2, s2, 6
	s_lshl_b32 s16, s1, 7
	s_add_u32 s16, s16, s2
	s_add_u32 s16, s16, 32
	s_cmpk_lt_u32 s16, 0x700
	s_cbranch_scc1 .Lip_e1_pk
	s_cmpk_lt_u32 s16, 0xa20
	s_cbranch_scc1 .Lip_e1_pt
	s_cmpk_lt_u32 s16, 0xba0
	s_cbranch_scc1 .Lip_e1_vt
	s_branch .Lip_e1_end
.Lip_e1_pk:
	s_mul_i32 s2, s0, 0x70000
	s_lshl_b32 s3, s16, 1
	s_add_u32 s2, s2, s3
	s_add_u32 s2, s2, 0x4400000
	s_add_u32 s6, s96, s2
	s_addc_u32 s7, s97, 0
	s_add_u32 s2, s6, 0x1c000
	s_addc_u32 s3, s7, 0
	s_cmpk_lt_u32 s16, 0x100
	s_cbranch_scc0 .Lip_e1_pk_noscale
	v_mul_f32_e32 v18, 0x3e38aa3b, v18
	v_mul_f32_e32 v19, 0x3e38aa3b, v19
	v_mul_f32_e32 v20, 0x3e38aa3b, v20
	v_mul_f32_e32 v21, 0x3e38aa3b, v21
	v_mul_f32_e32 v22, 0x3e38aa3b, v22
	v_mul_f32_e32 v23, 0x3e38aa3b, v23
	v_mul_f32_e32 v24, 0x3e38aa3b, v24
	v_mul_f32_e32 v25, 0x3e38aa3b, v25
	v_mul_f32_e32 v26, 0x3e38aa3b, v26
	v_mul_f32_e32 v27, 0x3e38aa3b, v27
	v_mul_f32_e32 v28, 0x3e38aa3b, v28
	v_mul_f32_e32 v29, 0x3e38aa3b, v29
	v_mul_f32_e32 v30, 0x3e38aa3b, v30
	v_mul_f32_e32 v31, 0x3e38aa3b, v31
	v_mul_f32_e32 v32, 0x3e38aa3b, v32
	v_mul_f32_e32 v33, 0x3e38aa3b, v33
	v_mul_f32_e32 v50, 0x3e38aa3b, v50
	v_mul_f32_e32 v51, 0x3e38aa3b, v51
	v_mul_f32_e32 v52, 0x3e38aa3b, v52
	v_mul_f32_e32 v53, 0x3e38aa3b, v53
	v_mul_f32_e32 v54, 0x3e38aa3b, v54
	v_mul_f32_e32 v55, 0x3e38aa3b, v55
	v_mul_f32_e32 v56, 0x3e38aa3b, v56
	v_mul_f32_e32 v57, 0x3e38aa3b, v57
	v_mul_f32_e32 v58, 0x3e38aa3b, v58
	v_mul_f32_e32 v59, 0x3e38aa3b, v59
	v_mul_f32_e32 v60, 0x3e38aa3b, v60
	v_mul_f32_e32 v61, 0x3e38aa3b, v61
	v_mul_f32_e32 v62, 0x3e38aa3b, v62
	v_mul_f32_e32 v63, 0x3e38aa3b, v63
	v_mul_f32_e32 v64, 0x3e38aa3b, v64
	v_mul_f32_e32 v65, 0x3e38aa3b, v65
.Lip_e1_pk_noscale:
	v_cvt_pk_bf16_f32 v66, v18, v19
	v_cvt_pk_bf16_f32 v67, v20, v21
	global_store_dwordx2 v110, v[66:67], s[6:7] offset:0
	v_cvt_pk_bf16_f32 v68, v22, v23
	v_cvt_pk_bf16_f32 v69, v24, v25
	global_store_dwordx2 v110, v[68:69], s[6:7] offset:16
	v_cvt_pk_bf16_f32 v70, v26, v27
	v_cvt_pk_bf16_f32 v71, v28, v29
	global_store_dwordx2 v110, v[70:71], s[6:7] offset:32
	v_cvt_pk_bf16_f32 v72, v30, v31
	v_cvt_pk_bf16_f32 v73, v32, v33
	global_store_dwordx2 v110, v[72:73], s[6:7] offset:48
	v_cvt_pk_bf16_f32 v66, v50, v51
	v_cvt_pk_bf16_f32 v67, v52, v53
	global_store_dwordx2 v110, v[66:67], s[2:3] offset:0
	v_cvt_pk_bf16_f32 v68, v54, v55
	v_cvt_pk_bf16_f32 v69, v56, v57
	global_store_dwordx2 v110, v[68:69], s[2:3] offset:16
	v_cvt_pk_bf16_f32 v70, v58, v59
	v_cvt_pk_bf16_f32 v71, v60, v61
	global_store_dwordx2 v110, v[70:71], s[2:3] offset:32
	v_cvt_pk_bf16_f32 v72, v62, v63
	v_cvt_pk_bf16_f32 v73, v64, v65
	global_store_dwordx2 v110, v[72:73], s[2:3] offset:48
	s_branch .Lip_e1_end
; DI u16 f2bf(float x) { return (u16)(pack2(x, 0.f) & 0xffffu); }
; DI int crow(int i, int h) { return (i & 3) + 8 * (i >> 2) + 4 * h; }
; DI void phase_inproj(const Params& p, int l, char* smem, int tid) {
;     ...
;   for (int it = blockIdx.x; it < 272 * 24; it += gridDim.x) {
;     ...
;         } else if (colb < 2592) {
; #pragma unroll
;           for (int i = 0; i < 16; i++) p.Pt[(size_t)(rowb + crow(i, h)) * PTW + col - 1792] = f2bf(acc[mb][nb][i]);
;         }
;       }
; #pragma unroll
;     for (int nb = 0; nb < 2; nb++) {
;       const int colb = n0 + wn * 64 + nb * 32;
;       if (colb >= 2592 && colb < 2976) {
;         const int rw = m0 + wm * 64;
;         float v[2][16];
; #pragma unroll
;         for (int mb = 0; mb < 2; mb++)
; #pragma unroll
;           for (int i = 0; i < 16; i++) v[mb][i] = acc[mb][nb][i];
;         vt_store32(v, (u16*)smem + w * (32 * 72), p.VtAD + ((size_t)(rw / SEQA) * 384 + colb - 2592) * SEQA + rw % SEQA, lane);
;       }
;     }
.Lip_e1_pt:
	s_mul_i32 s2, s0, 0x32000
	s_sub_u32 s3, s16, 0x700
	s_lshl_b32 s3, s3, 1
	s_add_u32 s2, s2, s3
	s_add_u32 s2, s2, 0xbb00000
	s_add_u32 s6, s96, s2
	s_addc_u32 s7, s97, 0
	s_add_u32 s2, s6, 0xc800
	s_addc_u32 s3, s7, 0
	v_cvt_pk_bf16_f32 v66, v18, v19
	v_cvt_pk_bf16_f32 v67, v20, v21
	global_store_dwordx2 v111, v[66:67], s[6:7] offset:0
	v_cvt_pk_bf16_f32 v68, v22, v23
	v_cvt_pk_bf16_f32 v69, v24, v25
	global_store_dwordx2 v111, v[68:69], s[6:7] offset:16
	v_cvt_pk_bf16_f32 v70, v26, v27
	v_cvt_pk_bf16_f32 v71, v28, v29
	global_store_dwordx2 v111, v[70:71], s[6:7] offset:32
	v_cvt_pk_bf16_f32 v72, v30, v31
	v_cvt_pk_bf16_f32 v73, v32, v33
	global_store_dwordx2 v111, v[72:73], s[6:7] offset:48
	v_cvt_pk_bf16_f32 v66, v50, v51
	v_cvt_pk_bf16_f32 v67, v52, v53
	global_store_dwordx2 v111, v[66:67], s[2:3] offset:0
	v_cvt_pk_bf16_f32 v68, v54, v55
	v_cvt_pk_bf16_f32 v69, v56, v57
	global_store_dwordx2 v111, v[68:69], s[2:3] offset:16
	v_cvt_pk_bf16_f32 v70, v58, v59
	v_cvt_pk_bf16_f32 v71, v60, v61
	global_store_dwordx2 v111, v[70:71], s[2:3] offset:32
	v_cvt_pk_bf16_f32 v72, v62, v63
	v_cvt_pk_bf16_f32 v73, v64, v65
	global_store_dwordx2 v111, v[72:73], s[2:3] offset:48
	s_branch .Lip_e1_end
.Lip_e1_vt:
	s_mul_hi_u32 s2, s0, 0x78787879
	s_lshr_b32 s2, s2, 4
	s_mul_i32 s3, s2, 34
	s_sub_u32 s3, s0, s3
	s_lshl_b32 s3, s3, 8
	s_mul_i32 s2, s2, 0x330000
	s_add_u32 s2, s2, s3
	s_sub_u32 s3, s16, 0xa20
	s_mul_i32 s3, s3, 0x2200
	s_add_u32 s2, s2, s3
	s_add_u32 s2, s2, 0xf020000
	s_add_u32 s6, s96, s2
	s_addc_u32 s7, s97, 0
	v_add_u32_e32 v74, 0x0, v112
	v_cvt_pk_bf16_f32 v66, v18, v18
	global_store_short v74, v66, s[6:7]
	v_add_u32_e32 v75, 0x2200, v112
	v_cvt_pk_bf16_f32 v68, v19, v19
	global_store_short v75, v68, s[6:7]
	v_add_u32_e32 v76, 0x4400, v112
	v_cvt_pk_bf16_f32 v70, v20, v20
	global_store_short v76, v70, s[6:7]
	v_add_u32_e32 v77, 0x6600, v112
	v_cvt_pk_bf16_f32 v72, v21, v21
	global_store_short v77, v72, s[6:7]
	v_add_u32_e32 v74, 0x11000, v112
	v_cvt_pk_bf16_f32 v66, v22, v22
	global_store_short v74, v66, s[6:7]
	v_add_u32_e32 v75, 0x13200, v112
	v_cvt_pk_bf16_f32 v68, v23, v23
	global_store_short v75, v68, s[6:7]
	v_add_u32_e32 v76, 0x15400, v112
	v_cvt_pk_bf16_f32 v70, v24, v24
	global_store_short v76, v70, s[6:7]
	v_add_u32_e32 v77, 0x17600, v112
	v_cvt_pk_bf16_f32 v72, v25, v25
	global_store_short v77, v72, s[6:7]
	v_add_u32_e32 v74, 0x22000, v112
	v_cvt_pk_bf16_f32 v66, v26, v26
	global_store_short v74, v66, s[6:7]
	v_add_u32_e32 v75, 0x24200, v112
	v_cvt_pk_bf16_f32 v68, v27, v27
	global_store_short v75, v68, s[6:7]
	v_add_u32_e32 v76, 0x26400, v112
	v_cvt_pk_bf16_f32 v70, v28, v28
	global_store_short v76, v70, s[6:7]
	v_add_u32_e32 v77, 0x28600, v112
	v_cvt_pk_bf16_f32 v72, v29, v29
	global_store_short v77, v72, s[6:7]
	v_add_u32_e32 v74, 0x33000, v112
	v_cvt_pk_bf16_f32 v66, v30, v30
	global_store_short v74, v66, s[6:7]
	v_add_u32_e32 v75, 0x35200, v112
	v_cvt_pk_bf16_f32 v68, v31, v31
	global_store_short v75, v68, s[6:7]
	v_add_u32_e32 v76, 0x37400, v112
	v_cvt_pk_bf16_f32 v70, v32, v32
	global_store_short v76, v70, s[6:7]
	v_add_u32_e32 v77, 0x39600, v112
	v_cvt_pk_bf16_f32 v72, v33, v33
	global_store_short v77, v72, s[6:7]
	v_add_u32_e32 v74, 0x40, v112
	v_cvt_pk_bf16_f32 v66, v50, v50
	global_store_short v74, v66, s[6:7]
	v_add_u32_e32 v75, 0x2240, v112
	v_cvt_pk_bf16_f32 v68, v51, v51
	global_store_short v75, v68, s[6:7]
	v_add_u32_e32 v76, 0x4440, v112
	v_cvt_pk_bf16_f32 v70, v52, v52
	global_store_short v76, v70, s[6:7]
	v_add_u32_e32 v77, 0x6640, v112
	v_cvt_pk_bf16_f32 v72, v53, v53
	global_store_short v77, v72, s[6:7]
	v_add_u32_e32 v74, 0x11040, v112
	v_cvt_pk_bf16_f32 v66, v54, v54
	global_store_short v74, v66, s[6:7]
	v_add_u32_e32 v75, 0x13240, v112
	v_cvt_pk_bf16_f32 v68, v55, v55
	global_store_short v75, v68, s[6:7]
	v_add_u32_e32 v76, 0x15440, v112
	v_cvt_pk_bf16_f32 v70, v56, v56
	global_store_short v76, v70, s[6:7]
	v_add_u32_e32 v77, 0x17640, v112
	v_cvt_pk_bf16_f32 v72, v57, v57
	global_store_short v77, v72, s[6:7]
	v_add_u32_e32 v74, 0x22040, v112
	v_cvt_pk_bf16_f32 v66, v58, v58
	global_store_short v74, v66, s[6:7]
	v_add_u32_e32 v75, 0x24240, v112
	v_cvt_pk_bf16_f32 v68, v59, v59
	global_store_short v75, v68, s[6:7]
	v_add_u32_e32 v76, 0x26440, v112
	v_cvt_pk_bf16_f32 v70, v60, v60
	global_store_short v76, v70, s[6:7]
	v_add_u32_e32 v77, 0x28640, v112
	v_cvt_pk_bf16_f32 v72, v61, v61
	global_store_short v77, v72, s[6:7]
	v_add_u32_e32 v74, 0x33040, v112
	v_cvt_pk_bf16_f32 v66, v62, v62
	global_store_short v74, v66, s[6:7]
	v_add_u32_e32 v75, 0x35240, v112
	v_cvt_pk_bf16_f32 v68, v63, v63
	global_store_short v75, v68, s[6:7]
	v_add_u32_e32 v76, 0x37440, v112
	v_cvt_pk_bf16_f32 v70, v64, v64
	global_store_short v76, v70, s[6:7]
	v_add_u32_e32 v77, 0x39640, v112
	v_cvt_pk_bf16_f32 v72, v65, v65
	global_store_short v77, v72, s[6:7]
.Lip_e1_end:
.Lip_epi_done:
	s_add_u32 s12, s12, s49
	s_branch .Lip_item
.Lip_done:
	s_waitcnt vmcnt(0) lgkmcnt(0)
.LBB0_550:
	s_getreg_b32 s2, hwreg(HW_REG_XCC_ID, 0, 4)
	s_waitcnt vmcnt(0)
	s_waitcnt vmcnt(63) expcnt(7) lgkmcnt(15)
	s_barrier
	s_and_saveexec_b64 s[0:1], s[92:93]
	s_cbranch_execz .LBB0_602
	v_mov_b32_e32 v149, s29
	s_waitcnt vmcnt(0) expcnt(0) lgkmcnt(0)
	flat_load_dword v2, v[148:149] sc0 sc1
	s_waitcnt vmcnt(0)
	v_mov_b32_e32 v151, s29
	flat_load_dword v0, v[150:151] sc0 sc1
	s_waitcnt vmcnt(0)
	s_and_b32 s12, s2, 15
	s_waitcnt lgkmcnt(0)
	v_cmp_eq_u32_e32 vcc, 0, v2
	s_and_saveexec_b64 s[4:5], vcc
	s_cbranch_execz .LBB0_566
	s_mov_b32 s2, 1
	s_branch .LBB0_554

; DI void phase_merge(const Params& p, int l, char* smem, int tid) {
;   const int lane = tid & 63, w = tid >> 6, r = lane & 31, h = lane >> 5, wm = w >> 1, wn = w & 1;
;   GemmLds* s = (GemmLds*)smem;
;   u16* ACC = p.Pk;
;   const bool dyn = (l == 0);
;   unsigned* qc = p.bar + 4096 + 320;
;   for (int it = (dyn ? fetch_item(qc, smem) : (int)blockIdx.x); it < 544 * 8; it = (dyn ? fetch_item(qc, smem) : it + (int)gridDim.x)) {
.LBB0_1140:
	s_or_b64 exec, exec, s[0:1]
	v_readlane_b32 s2, v254, 17
	v_readlane_b32 s3, v254, 18
	v_mov_b32_e32 v0, v206
	s_andn2_b64 vcc, exec, s[2:3]
	v_cndmask_b32_e64 v2, 0, 1, s[2:3]
	v_cmp_ne_u32_e64 s[0:1], 1, v2
	v_mov_b32_e32 v149, s48
	s_waitcnt lgkmcnt(0)
	s_barrier
	v_readlane_b32 s18, v254, 19
	v_and_b32_e32 v147, 63, v206
	v_lshrrev_b32_e32 v149, 6, v206
	v_lshrrev_b32_e32 v151, 3, v147
	v_lshl_add_u32 v151, v149, 5, v151
	v_lshlrev_b32_e32 v151, 11, v151
	v_and_b32_e32 v153, 7, v147
	v_lshrrev_b32_e32 v147, 4, v147
	v_xor_b32_e32 v153, v153, v147
	v_lshl_or_b32 v200, v153, 4, v151
	v_xor_b32_e32 v201, 64, v200
	v_add_u32_e32 v201, 16384, v201
	v_add_u32_e32 v202, 32768, v200
	v_add_u32_e32 v203, 32768, v201
	v_and_b32_e32 v147, 63, v206
	v_lshrrev_b32_e32 v149, 6, v206
	v_lshrrev_b32_e32 v151, 3, v147
	v_lshl_add_u32 v151, v149, 5, v151
	v_lshlrev_b32_e32 v151, 9, v151
	v_and_b32_e32 v153, 7, v147
	v_lshrrev_b32_e32 v147, 4, v147
	v_xor_b32_e32 v153, v153, v147
	v_lshl_or_b32 v130, v153, 4, v151
	v_xor_b32_e32 v131, 64, v130
	v_add_u32_e32 v131, 4096, v131
	v_add_u32_e32 v132, 8192, v130
	v_add_u32_e32 v133, 8192, v131
	v_lshrrev_b32_e32 v204, 6, v206
	v_and_b32_e32 v147, 31, v206
	v_bfe_u32 v149, v206, 5, 1
	v_bfe_u32 v151, v147, 1, 3
	v_xor_b32_e32 v151, v151, v149
	v_lshlrev_b32_e32 v151, 4, v151
	v_lshl_or_b32 v151, v147, 7, v151
	v_lshrrev_b32_e32 v153, 7, v206
	v_lshl_add_u32 v138, v153, 13, v151
	v_bfe_u32 v153, v206, 6, 1
	v_lshl_add_u32 v142, v153, 13, v151
	v_add_u32_e32 v142, 0x4000, v142
	v_xor_b32_e32 v139, 32, v138
	v_xor_b32_e32 v143, 32, v142
	v_xor_b32_e32 v140, 64, v138
	v_xor_b32_e32 v144, 64, v142
	v_xor_b32_e32 v141, 96, v138
	v_xor_b32_e32 v145, 96, v142
	v_and_b32_e32 v147, 31, v206
	v_lshrrev_b32_e32 v149, 7, v206
	v_lshl_add_u32 v147, v149, 6, v147
	v_lshlrev_b32_e32 v147, 11, v147
	v_bfe_u32 v149, v206, 6, 1
	v_lshlrev_b32_e32 v149, 7, v149
	v_bfe_u32 v151, v206, 5, 1
	v_lshl_or_b32 v149, v151, 3, v149
	v_or_b32_e32 v146, v147, v149
	v_lshrrev_b32_e32 v147, 6, v206
	v_mul_u32_u24_e32 v147, 0x2400, v147
	v_and_b32_e32 v149, 31, v206
	v_mul_u32_u24_e32 v149, 0x90, v149
	v_bfe_u32 v151, v206, 5, 1
	v_lshl_add_u32 v149, v151, 3, v149
	v_add_u32_e32 v134, v147, v149
	v_bfe_u32 v149, v206, 3, 3
	v_mul_u32_u24_e32 v149, 0x90, v149
	v_and_b32_e32 v151, 7, v206
	v_lshl_add_u32 v149, v151, 4, v149
	v_add_u32_e32 v135, v147, v149
	v_bfe_u32 v147, v206, 3, 3
	v_lshrrev_b32_e32 v149, 7, v206
	v_lshl_add_u32 v147, v149, 6, v147
	v_mul_u32_u24_e32 v147, 0x800, v147
	v_bfe_u32 v149, v206, 6, 1
	v_lshlrev_b32_e32 v149, 7, v149
	v_and_b32_e32 v151, 7, v206
	v_lshl_or_b32 v149, v151, 4, v149
	v_add_u32_e32 v136, v147, v149
	v_readfirstlane_b32 s10, v204
	s_lshl_b32 s10, s10, 12
	s_lshl_b32 s6, s18, 23
	s_add_u32 s14, s96, 0x1b720000
	s_addc_u32 s15, s97, 0
	s_add_u32 s14, s14, s6
	s_addc_u32 s15, s15, 0
	s_lshl_b32 s6, s18, 21
	s_add_u32 s16, s96, 0x1c800000
	s_addc_u32 s17, s97, 0
	s_add_u32 s16, s16, s6
	s_addc_u32 s17, s17, 0
	s_mov_b32 s12, s48

; DI void phase_merge(const Params& p, int l, char* smem, int tid) {
;     ...
;   for (int it = (dyn ? fetch_item(qc, smem) : (int)blockIdx.x); it < 544 * 8; it = (dyn ? fetch_item(qc, smem) : it + (int)gridDim.x)) {
;     const int mt = it >> 3, nt = it & 7, m0 = mt * 64, n0 = nt * 128;
;     if (l == 1 && (mt % 68) < 4) continue;
.Lmg_static:
	s_barrier
	s_cmpk_lt_u32 s12, 0x800
	s_cbranch_scc0 .Lmg_done
	s_lshr_b32 s6, s12, 8
	s_mul_i32 s6, s6, 34
	s_bfe_u32 s7, s12, 0x50003
	s_add_u32 s19, s6, s7
	s_add_u32 s19, s19, 2
	s_and_b32 s13, s12, 7

; #define G_STORE(S, bf) { *(uint4*)&s->a[bf][srow][skc] = S##a0; *(uint4*)&s->a[bf][srow + 32][skc] = S##a1; \
;     if (MB == 2) { *(uint4*)&s->a[bf][srow + 64][skc] = S##a2; *(uint4*)&s->a[bf][srow + 96][skc] = S##a3; } \
;     *(uint4*)&s->b[bf][srow][skc] = S##b0; *(uint4*)&s->b[bf][srow + 32][skc] = S##b1; *(uint4*)&s->b[bf][srow + 64][skc] = S##b2; *(uint4*)&s->b[bf][srow + 96][skc] = S##b3; }
; template <int MB, bool PF2 = true>
; DI void gemm_main(const u16* __restrict__ A, int lda, const u16* __restrict__ B, int ldb, int K, f32x16 (&acc)[MB][2], GemmLds* s, int tid) {
;     ...
;   int KT = K >> 6;
;   asm volatile("" : "+s"(KT));
;   __syncthreads();
;   G_LOAD(p, 0); G_STORE(p, 0);
;   if (!PF2) {
;     __syncthreads();
;     for (int kt = 0; kt < KT; kt++) {
;       const int buf = kt & 1;
;       if (kt + 1 < KT) G_LOAD(p, (kt + 1) * 64);
;       if (buf) { G_COMPUTE(1); } else { G_COMPUTE(0); }
;       if (kt + 1 < KT) { if (buf) { G_STORE(p, 0); } else { G_STORE(p, 1); } }
;       __syncthreads();
;     }
;     return;
;   }
;   const int klast = K - 64;
;   G_LOAD(p, 64);
;   __syncthreads();
;   for (int kt = 0; kt < KT; kt += 2) {
;     { const int k2 = min((kt + 2) * 64, klast); G_LOAD(q, k2); }
;     __builtin_amdgcn_sched_barrier(0);
;     G_COMPUTE(0);
;     G_STORE(p, 1);
;     __syncthreads();
;     { const int k3 = min((kt + 3) * 64, klast); G_LOAD(p, k3); }
;     __builtin_amdgcn_sched_barrier(0);
;     G_COMPUTE(1);
;     G_STORE(q, 0);
;     __syncthreads();
;   }
; DI void phase_merge(const Params& p, int l, char* smem, int tid) {
;     ...
;         f32x16 m[1][2]; zero_acc<1>(m);
;         gemm_main<1>(p.xn + (size_t)m0 * 1024, 1024, p.WtM + (size_t)l * 4096 * 1024 + ((size_t)i * 1024 + n0) * 1024, 1024, 1024, m, s, tid);
.Lmg_seg:
	v_mov_b32_e32 v66, 0
	v_mov_b32_e32 v67, 0
	v_mov_b32_e32 v68, 0
	v_mov_b32_e32 v69, 0
	v_mov_b32_e32 v70, 0
	v_mov_b32_e32 v71, 0
	v_mov_b32_e32 v72, 0
	v_mov_b32_e32 v73, 0
	v_mov_b32_e32 v74, 0
	v_mov_b32_e32 v75, 0
	v_mov_b32_e32 v76, 0
	v_mov_b32_e32 v77, 0
	v_mov_b32_e32 v78, 0
	v_mov_b32_e32 v79, 0
	v_mov_b32_e32 v80, 0
	v_mov_b32_e32 v81, 0
	v_mov_b32_e32 v82, 0
	v_mov_b32_e32 v83, 0
	v_mov_b32_e32 v84, 0
	v_mov_b32_e32 v85, 0
	v_mov_b32_e32 v86, 0
	v_mov_b32_e32 v87, 0
	v_mov_b32_e32 v88, 0
	v_mov_b32_e32 v89, 0
	v_mov_b32_e32 v90, 0
	v_mov_b32_e32 v91, 0
	v_mov_b32_e32 v92, 0
	v_mov_b32_e32 v93, 0
	v_mov_b32_e32 v94, 0
	v_mov_b32_e32 v95, 0
	v_mov_b32_e32 v96, 0
	v_mov_b32_e32 v97, 0
	v_mov_b32_e32 v98, 0
	v_mov_b32_e32 v99, 0
	v_mov_b32_e32 v100, 0
	v_mov_b32_e32 v101, 0
	v_mov_b32_e32 v102, 0
	v_mov_b32_e32 v103, 0
	v_mov_b32_e32 v104, 0
	v_mov_b32_e32 v105, 0
	v_mov_b32_e32 v106, 0
	v_mov_b32_e32 v107, 0
	v_mov_b32_e32 v108, 0
	v_mov_b32_e32 v109, 0
	v_mov_b32_e32 v110, 0
	v_mov_b32_e32 v111, 0
	v_mov_b32_e32 v112, 0
	v_mov_b32_e32 v113, 0
	v_mov_b32_e32 v114, 0
	v_mov_b32_e32 v115, 0
	v_mov_b32_e32 v116, 0
	v_mov_b32_e32 v117, 0
	v_mov_b32_e32 v118, 0
	v_mov_b32_e32 v119, 0
	v_mov_b32_e32 v120, 0
	v_mov_b32_e32 v121, 0
	v_mov_b32_e32 v122, 0
	v_mov_b32_e32 v123, 0
	v_mov_b32_e32 v124, 0
	v_mov_b32_e32 v125, 0
	v_mov_b32_e32 v126, 0
	v_mov_b32_e32 v127, 0
	v_mov_b32_e32 v128, 0
	v_mov_b32_e32 v129, 0
	s_waitcnt vmcnt(0) lgkmcnt(0)
	s_barrier
	ds_read_b128 v[224:227], v138 offset:0
	ds_read_b128 v[232:235], v142 offset:0
	ds_read_b128 v[228:231], v138 offset:4096
	ds_read_b128 v[236:239], v142 offset:4096
	s_add_u32 m0, s10, 0x8000
	s_nop 0
	global_load_lds_dwordx4 v200, s[4:5]
	s_add_u32 m0, s10, 0x8400
	s_nop 0
	global_load_lds_dwordx4 v201, s[4:5]
	s_add_u32 m0, s10, 0x8800
	s_nop 0
	global_load_lds_dwordx4 v202, s[4:5]
	s_add_u32 m0, s10, 0x8c00
	s_nop 0
	global_load_lds_dwordx4 v203, s[4:5]
	s_add_u32 s4, s4, 128
	s_addc_u32 s5, s5, 0
	s_mov_b32 s11, 7
.Lmgm_loop:
	ds_read_b128 v[240:243], v139 offset:0
	ds_read_b128 v[192:195], v143 offset:0
	ds_read_b128 v[188:191], v139 offset:4096
	ds_read_b128 v[196:199], v143 offset:4096
	s_waitcnt lgkmcnt(4)
	s_add_u32 m0, s10, 0xc000
	v_mfma_f32_32x32x16_bf16 v[66:81], v[232:235], v[224:227], v[66:81]
	global_load_lds_dwordx4 v200, s[8:9]
	s_add_u32 m0, s10, 0xc400
	v_mfma_f32_32x32x16_bf16 v[82:97], v[236:239], v[224:227], v[82:97]
	global_load_lds_dwordx4 v201, s[8:9]
	s_add_u32 m0, s10, 0xc800
	v_mfma_f32_32x32x16_bf16 v[98:113], v[232:235], v[228:231], v[98:113]
	global_load_lds_dwordx4 v202, s[8:9]
	s_add_u32 m0, s10, 0xcc00
	v_mfma_f32_32x32x16_bf16 v[114:129], v[236:239], v[228:231], v[114:129]
	global_load_lds_dwordx4 v203, s[8:9]
	s_add_u32 s8, s8, 128
	s_addc_u32 s9, s9, 0
	ds_read_b128 v[224:227], v140 offset:0
	ds_read_b128 v[232:235], v144 offset:0
	ds_read_b128 v[228:231], v140 offset:4096
	ds_read_b128 v[236:239], v144 offset:4096
	s_waitcnt lgkmcnt(4)
	v_mfma_f32_32x32x16_bf16 v[66:81], v[192:195], v[240:243], v[66:81]
	v_mfma_f32_32x32x16_bf16 v[82:97], v[196:199], v[240:243], v[82:97]
	v_mfma_f32_32x32x16_bf16 v[98:113], v[192:195], v[188:191], v[98:113]
	v_mfma_f32_32x32x16_bf16 v[114:129], v[196:199], v[188:191], v[114:129]
	ds_read_b128 v[240:243], v141 offset:0
	ds_read_b128 v[192:195], v145 offset:0
	ds_read_b128 v[188:191], v141 offset:4096
	ds_read_b128 v[196:199], v145 offset:4096
	s_waitcnt lgkmcnt(4)
	v_mfma_f32_32x32x16_bf16 v[66:81], v[232:235], v[224:227], v[66:81]
	v_mfma_f32_32x32x16_bf16 v[82:97], v[236:239], v[224:227], v[82:97]
	v_mfma_f32_32x32x16_bf16 v[98:113], v[232:235], v[228:231], v[98:113]
	v_mfma_f32_32x32x16_bf16 v[114:129], v[236:239], v[228:231], v[114:129]
	s_waitcnt vmcnt(0) lgkmcnt(0)
	s_barrier
	ds_read_b128 v[224:227], v138 offset:32768
	ds_read_b128 v[232:235], v142 offset:32768
	ds_read_b128 v[228:231], v138 offset:36864
	ds_read_b128 v[236:239], v142 offset:36864
	s_cmp_eq_u32 s11, 0
	s_cbranch_scc1 .Lmgm_hold0
	s_add_u32 m0, s10, 0x0
	v_mfma_f32_32x32x16_bf16 v[66:81], v[192:195], v[240:243], v[66:81]
	global_load_lds_dwordx4 v200, s[4:5]
	s_add_u32 m0, s10, 0x400
	v_mfma_f32_32x32x16_bf16 v[82:97], v[196:199], v[240:243], v[82:97]
	global_load_lds_dwordx4 v201, s[4:5]
	s_add_u32 m0, s10, 0x800
	v_mfma_f32_32x32x16_bf16 v[98:113], v[192:195], v[188:191], v[98:113]
	global_load_lds_dwordx4 v202, s[4:5]
	s_add_u32 m0, s10, 0xc00
	v_mfma_f32_32x32x16_bf16 v[114:129], v[196:199], v[188:191], v[114:129]
	global_load_lds_dwordx4 v203, s[4:5]
	s_add_u32 s4, s4, 128
	s_addc_u32 s5, s5, 0
	s_branch .Lmgm_held0
; #define G_STORE(S, bf) { *(uint4*)&s->a[bf][srow][skc] = S##a0; *(uint4*)&s->a[bf][srow + 32][skc] = S##a1; \
;     if (MB == 2) { *(uint4*)&s->a[bf][srow + 64][skc] = S##a2; *(uint4*)&s->a[bf][srow + 96][skc] = S##a3; } \
;     *(uint4*)&s->b[bf][srow][skc] = S##b0; *(uint4*)&s->b[bf][srow + 32][skc] = S##b1; *(uint4*)&s->b[bf][srow + 64][skc] = S##b2; *(uint4*)&s->b[bf][srow + 96][skc] = S##b3; }
; template <int MB, bool PF2 = true>
; DI void gemm_main(const u16* __restrict__ A, int lda, const u16* __restrict__ B, int ldb, int K, f32x16 (&acc)[MB][2], GemmLds* s, int tid) {
;     ...
;   for (int kt = 0; kt < KT; kt += 2) {
;     { const int k2 = min((kt + 2) * 64, klast); G_LOAD(q, k2); }
;     __builtin_amdgcn_sched_barrier(0);
;     G_COMPUTE(0);
;     G_STORE(p, 1);
;     __syncthreads();
;     { const int k3 = min((kt + 3) * 64, klast); G_LOAD(p, k3); }
;     __builtin_amdgcn_sched_barrier(0);
;     G_COMPUTE(1);
;     G_STORE(q, 0);
;     __syncthreads();
;   }
.Lmgm_hold0:
	v_mfma_f32_32x32x16_bf16 v[66:81], v[192:195], v[240:243], v[66:81]
	v_mfma_f32_32x32x16_bf16 v[82:97], v[196:199], v[240:243], v[82:97]
	v_mfma_f32_32x32x16_bf16 v[98:113], v[192:195], v[188:191], v[98:113]
	v_mfma_f32_32x32x16_bf16 v[114:129], v[196:199], v[188:191], v[114:129]
.Lmgm_held0:
	s_cmp_eq_u32 s11, 0
	s_cbranch_scc1 .Lmgm_last
	ds_read_b128 v[240:243], v139 offset:32768
	ds_read_b128 v[192:195], v143 offset:32768
	ds_read_b128 v[188:191], v139 offset:36864
	ds_read_b128 v[196:199], v143 offset:36864
	s_waitcnt lgkmcnt(4)
	s_add_u32 m0, s10, 0x4000
	v_mfma_f32_32x32x16_bf16 v[66:81], v[232:235], v[224:227], v[66:81]
	global_load_lds_dwordx4 v200, s[8:9]
	s_add_u32 m0, s10, 0x4400
	v_mfma_f32_32x32x16_bf16 v[82:97], v[236:239], v[224:227], v[82:97]
	global_load_lds_dwordx4 v201, s[8:9]
	s_add_u32 m0, s10, 0x4800
	v_mfma_f32_32x32x16_bf16 v[98:113], v[232:235], v[228:231], v[98:113]
	global_load_lds_dwordx4 v202, s[8:9]
	s_add_u32 m0, s10, 0x4c00
	v_mfma_f32_32x32x16_bf16 v[114:129], v[236:239], v[228:231], v[114:129]
	global_load_lds_dwordx4 v203, s[8:9]
	s_add_u32 s8, s8, 128
	s_addc_u32 s9, s9, 0
	ds_read_b128 v[224:227], v140 offset:32768
	ds_read_b128 v[232:235], v144 offset:32768
	ds_read_b128 v[228:231], v140 offset:36864
	ds_read_b128 v[236:239], v144 offset:36864
	s_waitcnt lgkmcnt(4)
	v_mfma_f32_32x32x16_bf16 v[66:81], v[192:195], v[240:243], v[66:81]
	v_mfma_f32_32x32x16_bf16 v[82:97], v[196:199], v[240:243], v[82:97]
	v_mfma_f32_32x32x16_bf16 v[98:113], v[192:195], v[188:191], v[98:113]
	v_mfma_f32_32x32x16_bf16 v[114:129], v[196:199], v[188:191], v[114:129]
	ds_read_b128 v[240:243], v141 offset:32768
	ds_read_b128 v[192:195], v145 offset:32768
	ds_read_b128 v[188:191], v141 offset:36864
	ds_read_b128 v[196:199], v145 offset:36864
	s_waitcnt lgkmcnt(4)
	v_mfma_f32_32x32x16_bf16 v[66:81], v[232:235], v[224:227], v[66:81]
	v_mfma_f32_32x32x16_bf16 v[82:97], v[236:239], v[224:227], v[82:97]
	v_mfma_f32_32x32x16_bf16 v[98:113], v[232:235], v[228:231], v[98:113]
	v_mfma_f32_32x32x16_bf16 v[114:129], v[236:239], v[228:231], v[114:129]
	s_waitcnt vmcnt(0) lgkmcnt(0)
	s_barrier
	ds_read_b128 v[224:227], v138 offset:0
	ds_read_b128 v[232:235], v142 offset:0
	ds_read_b128 v[228:231], v138 offset:4096
	ds_read_b128 v[236:239], v142 offset:4096
	s_add_u32 m0, s10, 0x8000
	v_mfma_f32_32x32x16_bf16 v[66:81], v[192:195], v[240:243], v[66:81]
	global_load_lds_dwordx4 v200, s[4:5]
	s_add_u32 m0, s10, 0x8400
	v_mfma_f32_32x32x16_bf16 v[82:97], v[196:199], v[240:243], v[82:97]
	global_load_lds_dwordx4 v201, s[4:5]
	s_add_u32 m0, s10, 0x8800
	v_mfma_f32_32x32x16_bf16 v[98:113], v[192:195], v[188:191], v[98:113]
	global_load_lds_dwordx4 v202, s[4:5]
	s_add_u32 m0, s10, 0x8c00
	v_mfma_f32_32x32x16_bf16 v[114:129], v[196:199], v[188:191], v[114:129]
	global_load_lds_dwordx4 v203, s[4:5]
	s_add_u32 s4, s4, 128
	s_addc_u32 s5, s5, 0
	s_sub_u32 s11, s11, 1
	s_branch .Lmgm_loop

; DI unsigned pack2(float a, float b) { f32v2 v = {a, b}; return __builtin_bit_cast(unsigned, __builtin_convertvector(v, bf16v2)); }
; DI float sigm_fast(float x) { return __builtin_amdgcn_rcpf(1.f + __expf(-x)); }
; #define G_STORE(S, bf) { *(uint4*)&s->a[bf][srow][skc] = S##a0; *(uint4*)&s->a[bf][srow + 32][skc] = S##a1; \
;     if (MB == 2) { *(uint4*)&s->a[bf][srow + 64][skc] = S##a2; *(uint4*)&s->a[bf][srow + 96][skc] = S##a3; } \
;     *(uint4*)&s->b[bf][srow][skc] = S##b0; *(uint4*)&s->b[bf][srow + 32][skc] = S##b1; *(uint4*)&s->b[bf][srow + 64][skc] = S##b2; *(uint4*)&s->b[bf][srow + 96][skc] = S##b3; }
; template <int MB, bool PF2 = true>
; DI void gemm_main(const u16* __restrict__ A, int lda, const u16* __restrict__ B, int ldb, int K, f32x16 (&acc)[MB][2], GemmLds* s, int tid) {
;     ...
;     G_COMPUTE(0);
;     G_STORE(p, 1);
;     __syncthreads();
;     { const int k3 = min((kt + 3) * 64, klast); G_LOAD(p, k3); }
;     __builtin_amdgcn_sched_barrier(0);
;     G_COMPUTE(1);
;     G_STORE(q, 0);
;     __syncthreads();
;   }
; DI void phase_merge(const Params& p, int l, char* smem, int tid) {
;     ...
; #pragma unroll
;         for (int b2 = 0; b2 < 2; b2++)
; #pragma unroll
;           for (int e = 0; e < 8; e++) sg[b2][e] = pack2(sigm_fast(m[0][b2][2 * e]), sigm_fast(m[0][b2][2 * e + 1]));
.Lmgm_nopf:
	ds_read_b128 v[240:243], v139 offset:32768
	ds_read_b128 v[192:195], v143 offset:32768
	ds_read_b128 v[188:191], v139 offset:36864
	ds_read_b128 v[196:199], v143 offset:36864
	s_waitcnt lgkmcnt(4)
	v_mfma_f32_32x32x16_bf16 v[66:81], v[232:235], v[224:227], v[66:81]
	v_mfma_f32_32x32x16_bf16 v[82:97], v[236:239], v[224:227], v[82:97]
	v_mfma_f32_32x32x16_bf16 v[98:113], v[232:235], v[228:231], v[98:113]
	v_mfma_f32_32x32x16_bf16 v[114:129], v[236:239], v[228:231], v[114:129]
	ds_read_b128 v[224:227], v140 offset:32768
	ds_read_b128 v[232:235], v144 offset:32768
	ds_read_b128 v[228:231], v140 offset:36864
	ds_read_b128 v[236:239], v144 offset:36864
	s_waitcnt lgkmcnt(4)
	v_mfma_f32_32x32x16_bf16 v[66:81], v[192:195], v[240:243], v[66:81]
	v_mfma_f32_32x32x16_bf16 v[82:97], v[196:199], v[240:243], v[82:97]
	v_mfma_f32_32x32x16_bf16 v[98:113], v[192:195], v[188:191], v[98:113]
	v_mfma_f32_32x32x16_bf16 v[114:129], v[196:199], v[188:191], v[114:129]
	ds_read_b128 v[240:243], v141 offset:32768
	ds_read_b128 v[192:195], v145 offset:32768
	ds_read_b128 v[188:191], v141 offset:36864
	ds_read_b128 v[196:199], v145 offset:36864
	s_waitcnt lgkmcnt(4)
	v_mfma_f32_32x32x16_bf16 v[66:81], v[232:235], v[224:227], v[66:81]
	v_mfma_f32_32x32x16_bf16 v[82:97], v[236:239], v[224:227], v[82:97]
	v_mfma_f32_32x32x16_bf16 v[98:113], v[232:235], v[228:231], v[98:113]
	v_mfma_f32_32x32x16_bf16 v[114:129], v[236:239], v[228:231], v[114:129]
	s_waitcnt lgkmcnt(0)
	s_barrier
	v_mfma_f32_32x32x16_bf16 v[66:81], v[192:195], v[240:243], v[66:81]
	v_mfma_f32_32x32x16_bf16 v[82:97], v[196:199], v[240:243], v[82:97]
	v_mfma_f32_32x32x16_bf16 v[98:113], v[192:195], v[188:191], v[98:113]
	v_mfma_f32_32x32x16_bf16 v[114:129], v[196:199], v[188:191], v[114:129]
	s_nop 7
	s_nop 7
	v_mul_f32_e32 v66, 0xbfb8aa3b, v66
	v_mul_f32_e32 v67, 0xbfb8aa3b, v67
	v_mul_f32_e32 v68, 0xbfb8aa3b, v68
	v_mul_f32_e32 v69, 0xbfb8aa3b, v69
	v_mul_f32_e32 v70, 0xbfb8aa3b, v70
	v_mul_f32_e32 v71, 0xbfb8aa3b, v71
	v_mul_f32_e32 v72, 0xbfb8aa3b, v72
	v_mul_f32_e32 v73, 0xbfb8aa3b, v73
	v_exp_f32_e32 v66, v66
	v_exp_f32_e32 v67, v67
	v_exp_f32_e32 v68, v68
	v_exp_f32_e32 v69, v69
	v_exp_f32_e32 v70, v70
	v_exp_f32_e32 v71, v71
	v_exp_f32_e32 v72, v72
	v_exp_f32_e32 v73, v73
	v_add_f32_e32 v66, 1.0, v66
	v_add_f32_e32 v67, 1.0, v67
	v_add_f32_e32 v68, 1.0, v68
	v_add_f32_e32 v69, 1.0, v69
	v_add_f32_e32 v70, 1.0, v70
	v_add_f32_e32 v71, 1.0, v71
	v_add_f32_e32 v72, 1.0, v72
	v_add_f32_e32 v73, 1.0, v73
	v_rcp_f32_e32 v66, v66
	v_rcp_f32_e32 v67, v67
	v_rcp_f32_e32 v68, v68
	v_rcp_f32_e32 v69, v69
	v_rcp_f32_e32 v70, v70
	v_rcp_f32_e32 v71, v71
	v_rcp_f32_e32 v72, v72
	v_rcp_f32_e32 v73, v73
	s_nop 0
	v_cvt_pk_bf16_f32 v156, v66, v67
	v_cvt_pk_bf16_f32 v157, v68, v69
	v_cvt_pk_bf16_f32 v158, v70, v71
	v_cvt_pk_bf16_f32 v159, v72, v73
	v_mul_f32_e32 v74, 0xbfb8aa3b, v74
	v_mul_f32_e32 v75, 0xbfb8aa3b, v75
	v_mul_f32_e32 v76, 0xbfb8aa3b, v76
	v_mul_f32_e32 v77, 0xbfb8aa3b, v77
	v_mul_f32_e32 v78, 0xbfb8aa3b, v78
	v_mul_f32_e32 v79, 0xbfb8aa3b, v79
	v_mul_f32_e32 v80, 0xbfb8aa3b, v80
	v_mul_f32_e32 v81, 0xbfb8aa3b, v81
	v_exp_f32_e32 v74, v74
	v_exp_f32_e32 v75, v75
	v_exp_f32_e32 v76, v76
	v_exp_f32_e32 v77, v77
	v_exp_f32_e32 v78, v78
	v_exp_f32_e32 v79, v79
	v_exp_f32_e32 v80, v80
	v_exp_f32_e32 v81, v81
	v_add_f32_e32 v74, 1.0, v74
	v_add_f32_e32 v75, 1.0, v75
	v_add_f32_e32 v76, 1.0, v76
	v_add_f32_e32 v77, 1.0, v77
	v_add_f32_e32 v78, 1.0, v78
	v_add_f32_e32 v79, 1.0, v79
	v_add_f32_e32 v80, 1.0, v80
	v_add_f32_e32 v81, 1.0, v81
	v_rcp_f32_e32 v74, v74
	v_rcp_f32_e32 v75, v75
	v_rcp_f32_e32 v76, v76
	v_rcp_f32_e32 v77, v77
	v_rcp_f32_e32 v78, v78
	v_rcp_f32_e32 v79, v79
	v_rcp_f32_e32 v80, v80
	v_rcp_f32_e32 v81, v81
	s_nop 0
	v_cvt_pk_bf16_f32 v160, v74, v75
	v_cvt_pk_bf16_f32 v161, v76, v77
	v_cvt_pk_bf16_f32 v162, v78, v79
	v_cvt_pk_bf16_f32 v163, v80, v81
	v_mul_f32_e32 v82, 0xbfb8aa3b, v82
	v_mul_f32_e32 v83, 0xbfb8aa3b, v83
	v_mul_f32_e32 v84, 0xbfb8aa3b, v84
	v_mul_f32_e32 v85, 0xbfb8aa3b, v85
	v_mul_f32_e32 v86, 0xbfb8aa3b, v86
	v_mul_f32_e32 v87, 0xbfb8aa3b, v87
	v_mul_f32_e32 v88, 0xbfb8aa3b, v88
	v_mul_f32_e32 v89, 0xbfb8aa3b, v89
	v_exp_f32_e32 v82, v82
	v_exp_f32_e32 v83, v83
	v_exp_f32_e32 v84, v84
	v_exp_f32_e32 v85, v85
	v_exp_f32_e32 v86, v86
	v_exp_f32_e32 v87, v87
	v_exp_f32_e32 v88, v88
	v_exp_f32_e32 v89, v89
	v_add_f32_e32 v82, 1.0, v82
	v_add_f32_e32 v83, 1.0, v83
	v_add_f32_e32 v84, 1.0, v84
	v_add_f32_e32 v85, 1.0, v85
	v_add_f32_e32 v86, 1.0, v86
	v_add_f32_e32 v87, 1.0, v87
	v_add_f32_e32 v88, 1.0, v88
	v_add_f32_e32 v89, 1.0, v89
	v_rcp_f32_e32 v82, v82
	v_rcp_f32_e32 v83, v83
	v_rcp_f32_e32 v84, v84
	v_rcp_f32_e32 v85, v85
	v_rcp_f32_e32 v86, v86
	v_rcp_f32_e32 v87, v87
	v_rcp_f32_e32 v88, v88
	v_rcp_f32_e32 v89, v89
	s_nop 0
	v_cvt_pk_bf16_f32 v164, v82, v83
	v_cvt_pk_bf16_f32 v165, v84, v85
	v_cvt_pk_bf16_f32 v166, v86, v87
	v_cvt_pk_bf16_f32 v167, v88, v89
	v_mul_f32_e32 v90, 0xbfb8aa3b, v90
	v_mul_f32_e32 v91, 0xbfb8aa3b, v91
	v_mul_f32_e32 v92, 0xbfb8aa3b, v92
	v_mul_f32_e32 v93, 0xbfb8aa3b, v93
	v_mul_f32_e32 v94, 0xbfb8aa3b, v94
	v_mul_f32_e32 v95, 0xbfb8aa3b, v95
	v_mul_f32_e32 v96, 0xbfb8aa3b, v96
	v_mul_f32_e32 v97, 0xbfb8aa3b, v97
	v_exp_f32_e32 v90, v90
	v_exp_f32_e32 v91, v91
	v_exp_f32_e32 v92, v92
	v_exp_f32_e32 v93, v93
	v_exp_f32_e32 v94, v94
	v_exp_f32_e32 v95, v95
	v_exp_f32_e32 v96, v96
	v_exp_f32_e32 v97, v97
	v_add_f32_e32 v90, 1.0, v90
	v_add_f32_e32 v91, 1.0, v91
	v_add_f32_e32 v92, 1.0, v92
	v_add_f32_e32 v93, 1.0, v93
	v_add_f32_e32 v94, 1.0, v94
	v_add_f32_e32 v95, 1.0, v95
	v_add_f32_e32 v96, 1.0, v96
	v_add_f32_e32 v97, 1.0, v97
; DI unsigned pack2(float a, float b) { f32v2 v = {a, b}; return __builtin_bit_cast(unsigned, __builtin_convertvector(v, bf16v2)); }
; DI float sigm_fast(float x) { return __builtin_amdgcn_rcpf(1.f + __expf(-x)); }
; DI void phase_merge(const Params& p, int l, char* smem, int tid) {
;     ...
;           for (int e = 0; e < 8; e++) sg[b2][e] = pack2(sigm_fast(m[0][b2][2 * e]), sigm_fast(m[0][b2][2 * e + 1]));
;       }
;       f32x16 t[1][2]; zero_acc<1>(t);
;       gemm_main<1>(p.G + (size_t)m0 * 1024 + i * 256, 1024, p.WtBr + ((size_t)l * 4 + i) * 1024 * 256 + (size_t)n0 * 256, 256, 256, t, s, tid);
	v_rcp_f32_e32 v90, v90
	v_rcp_f32_e32 v91, v91
	v_rcp_f32_e32 v92, v92
	v_rcp_f32_e32 v93, v93
	v_rcp_f32_e32 v94, v94
	v_rcp_f32_e32 v95, v95
	v_rcp_f32_e32 v96, v96
	v_rcp_f32_e32 v97, v97
	s_nop 0
	v_cvt_pk_bf16_f32 v168, v90, v91
	v_cvt_pk_bf16_f32 v169, v92, v93
	v_cvt_pk_bf16_f32 v170, v94, v95
	v_cvt_pk_bf16_f32 v171, v96, v97
	v_mul_f32_e32 v98, 0xbfb8aa3b, v98
	v_mul_f32_e32 v99, 0xbfb8aa3b, v99
	v_mul_f32_e32 v100, 0xbfb8aa3b, v100
	v_mul_f32_e32 v101, 0xbfb8aa3b, v101
	v_mul_f32_e32 v102, 0xbfb8aa3b, v102
	v_mul_f32_e32 v103, 0xbfb8aa3b, v103
	v_mul_f32_e32 v104, 0xbfb8aa3b, v104
	v_mul_f32_e32 v105, 0xbfb8aa3b, v105
	v_exp_f32_e32 v98, v98
	v_exp_f32_e32 v99, v99
	v_exp_f32_e32 v100, v100
	v_exp_f32_e32 v101, v101
	v_exp_f32_e32 v102, v102
	v_exp_f32_e32 v103, v103
	v_exp_f32_e32 v104, v104
	v_exp_f32_e32 v105, v105
	v_add_f32_e32 v98, 1.0, v98
	v_add_f32_e32 v99, 1.0, v99
	v_add_f32_e32 v100, 1.0, v100
	v_add_f32_e32 v101, 1.0, v101
	v_add_f32_e32 v102, 1.0, v102
	v_add_f32_e32 v103, 1.0, v103
	v_add_f32_e32 v104, 1.0, v104
	v_add_f32_e32 v105, 1.0, v105
	v_rcp_f32_e32 v98, v98
	v_rcp_f32_e32 v99, v99
	v_rcp_f32_e32 v100, v100
	v_rcp_f32_e32 v101, v101
	v_rcp_f32_e32 v102, v102
	v_rcp_f32_e32 v103, v103
	v_rcp_f32_e32 v104, v104
	v_rcp_f32_e32 v105, v105
	s_nop 0
	v_cvt_pk_bf16_f32 v172, v98, v99
	v_cvt_pk_bf16_f32 v173, v100, v101
	v_cvt_pk_bf16_f32 v174, v102, v103
	v_cvt_pk_bf16_f32 v175, v104, v105
	v_mul_f32_e32 v106, 0xbfb8aa3b, v106
	v_mul_f32_e32 v107, 0xbfb8aa3b, v107
	v_mul_f32_e32 v108, 0xbfb8aa3b, v108
	v_mul_f32_e32 v109, 0xbfb8aa3b, v109
	v_mul_f32_e32 v110, 0xbfb8aa3b, v110
	v_mul_f32_e32 v111, 0xbfb8aa3b, v111
	v_mul_f32_e32 v112, 0xbfb8aa3b, v112
	v_mul_f32_e32 v113, 0xbfb8aa3b, v113
	v_exp_f32_e32 v106, v106
	v_exp_f32_e32 v107, v107
	v_exp_f32_e32 v108, v108
	v_exp_f32_e32 v109, v109
	v_exp_f32_e32 v110, v110
	v_exp_f32_e32 v111, v111
	v_exp_f32_e32 v112, v112
	v_exp_f32_e32 v113, v113
	v_add_f32_e32 v106, 1.0, v106
	v_add_f32_e32 v107, 1.0, v107
	v_add_f32_e32 v108, 1.0, v108
	v_add_f32_e32 v109, 1.0, v109
	v_add_f32_e32 v110, 1.0, v110
	v_add_f32_e32 v111, 1.0, v111
	v_add_f32_e32 v112, 1.0, v112
	v_add_f32_e32 v113, 1.0, v113
	v_rcp_f32_e32 v106, v106
	v_rcp_f32_e32 v107, v107
	v_rcp_f32_e32 v108, v108
	v_rcp_f32_e32 v109, v109
	v_rcp_f32_e32 v110, v110
	v_rcp_f32_e32 v111, v111
	v_rcp_f32_e32 v112, v112
	v_rcp_f32_e32 v113, v113
	s_nop 0
	v_cvt_pk_bf16_f32 v176, v106, v107
	v_cvt_pk_bf16_f32 v177, v108, v109
	v_cvt_pk_bf16_f32 v178, v110, v111
	v_cvt_pk_bf16_f32 v179, v112, v113
	v_mul_f32_e32 v114, 0xbfb8aa3b, v114
	v_mul_f32_e32 v115, 0xbfb8aa3b, v115
	v_mul_f32_e32 v116, 0xbfb8aa3b, v116
	v_mul_f32_e32 v117, 0xbfb8aa3b, v117
	v_mul_f32_e32 v118, 0xbfb8aa3b, v118
	v_mul_f32_e32 v119, 0xbfb8aa3b, v119
	v_mul_f32_e32 v120, 0xbfb8aa3b, v120
	v_mul_f32_e32 v121, 0xbfb8aa3b, v121
	v_exp_f32_e32 v114, v114
	v_exp_f32_e32 v115, v115
	v_exp_f32_e32 v116, v116
	v_exp_f32_e32 v117, v117
	v_exp_f32_e32 v118, v118
	v_exp_f32_e32 v119, v119
	v_exp_f32_e32 v120, v120
	v_exp_f32_e32 v121, v121
	v_add_f32_e32 v114, 1.0, v114
	v_add_f32_e32 v115, 1.0, v115
	v_add_f32_e32 v116, 1.0, v116
	v_add_f32_e32 v117, 1.0, v117
	v_add_f32_e32 v118, 1.0, v118
	v_add_f32_e32 v119, 1.0, v119
	v_add_f32_e32 v120, 1.0, v120
	v_add_f32_e32 v121, 1.0, v121
	v_rcp_f32_e32 v114, v114
	v_rcp_f32_e32 v115, v115
	v_rcp_f32_e32 v116, v116
	v_rcp_f32_e32 v117, v117
	v_rcp_f32_e32 v118, v118
	v_rcp_f32_e32 v119, v119
	v_rcp_f32_e32 v120, v120
	v_rcp_f32_e32 v121, v121
	s_nop 0
	v_cvt_pk_bf16_f32 v180, v114, v115
	v_cvt_pk_bf16_f32 v181, v116, v117
	v_cvt_pk_bf16_f32 v182, v118, v119
	v_cvt_pk_bf16_f32 v183, v120, v121
	v_mul_f32_e32 v122, 0xbfb8aa3b, v122
	v_mul_f32_e32 v123, 0xbfb8aa3b, v123
	v_mul_f32_e32 v124, 0xbfb8aa3b, v124
	v_mul_f32_e32 v125, 0xbfb8aa3b, v125
	v_mul_f32_e32 v126, 0xbfb8aa3b, v126
	v_mul_f32_e32 v127, 0xbfb8aa3b, v127
	v_mul_f32_e32 v128, 0xbfb8aa3b, v128
	v_mul_f32_e32 v129, 0xbfb8aa3b, v129
	v_exp_f32_e32 v122, v122
	v_exp_f32_e32 v123, v123
	v_exp_f32_e32 v124, v124
	v_exp_f32_e32 v125, v125
	v_exp_f32_e32 v126, v126
	v_exp_f32_e32 v127, v127
	v_exp_f32_e32 v128, v128
	v_exp_f32_e32 v129, v129
	v_add_f32_e32 v122, 1.0, v122
	v_add_f32_e32 v123, 1.0, v123
	v_add_f32_e32 v124, 1.0, v124
	v_add_f32_e32 v125, 1.0, v125
	v_add_f32_e32 v126, 1.0, v126
	v_add_f32_e32 v127, 1.0, v127
	v_add_f32_e32 v128, 1.0, v128
	v_add_f32_e32 v129, 1.0, v129
	v_rcp_f32_e32 v122, v122
	v_rcp_f32_e32 v123, v123
	v_rcp_f32_e32 v124, v124
	v_rcp_f32_e32 v125, v125
	v_rcp_f32_e32 v126, v126
	v_rcp_f32_e32 v127, v127
	v_rcp_f32_e32 v128, v128
	v_rcp_f32_e32 v129, v129
	s_nop 0
	v_cvt_pk_bf16_f32 v184, v122, v123
	v_cvt_pk_bf16_f32 v185, v124, v125
	v_cvt_pk_bf16_f32 v186, v126, v127
	v_cvt_pk_bf16_f32 v187, v128, v129
	s_add_u32 s13, s13, 1
	v_mov_b32_e32 v66, 0
	v_mov_b32_e32 v67, 0
	v_mov_b32_e32 v68, 0
	v_mov_b32_e32 v69, 0
	v_mov_b32_e32 v70, 0
	v_mov_b32_e32 v71, 0
	v_mov_b32_e32 v72, 0
	v_mov_b32_e32 v73, 0
	v_mov_b32_e32 v74, 0
	v_mov_b32_e32 v75, 0
	v_mov_b32_e32 v76, 0
	v_mov_b32_e32 v77, 0
	v_mov_b32_e32 v78, 0
	v_mov_b32_e32 v79, 0
	v_mov_b32_e32 v80, 0
	v_mov_b32_e32 v81, 0
	v_mov_b32_e32 v82, 0
	v_mov_b32_e32 v83, 0
	v_mov_b32_e32 v84, 0
	v_mov_b32_e32 v85, 0
	v_mov_b32_e32 v86, 0
	v_mov_b32_e32 v87, 0
	v_mov_b32_e32 v88, 0
	v_mov_b32_e32 v89, 0
	v_mov_b32_e32 v90, 0
	v_mov_b32_e32 v91, 0
	v_mov_b32_e32 v92, 0
	v_mov_b32_e32 v93, 0
	v_mov_b32_e32 v94, 0
	v_mov_b32_e32 v95, 0
	v_mov_b32_e32 v96, 0
	v_mov_b32_e32 v97, 0
	v_mov_b32_e32 v98, 0
	v_mov_b32_e32 v99, 0
	v_mov_b32_e32 v100, 0
	v_mov_b32_e32 v101, 0
	v_mov_b32_e32 v102, 0
	v_mov_b32_e32 v103, 0
	v_mov_b32_e32 v104, 0
	v_mov_b32_e32 v105, 0
	v_mov_b32_e32 v106, 0
	v_mov_b32_e32 v107, 0
	v_mov_b32_e32 v108, 0
	v_mov_b32_e32 v109, 0
	v_mov_b32_e32 v110, 0
	v_mov_b32_e32 v111, 0
	v_mov_b32_e32 v112, 0
	v_mov_b32_e32 v113, 0
	v_mov_b32_e32 v114, 0
	v_mov_b32_e32 v115, 0
	v_mov_b32_e32 v116, 0
	v_mov_b32_e32 v117, 0
	v_mov_b32_e32 v118, 0
	v_mov_b32_e32 v119, 0
	v_mov_b32_e32 v120, 0
	v_mov_b32_e32 v121, 0
	v_mov_b32_e32 v122, 0
	v_mov_b32_e32 v123, 0
	v_mov_b32_e32 v124, 0
	v_mov_b32_e32 v125, 0
	v_mov_b32_e32 v126, 0
	v_mov_b32_e32 v127, 0
	v_mov_b32_e32 v128, 0
	v_mov_b32_e32 v129, 0
	s_waitcnt vmcnt(0) lgkmcnt(0)
	s_barrier
	ds_read_b128 v[224:227], v138 offset:0
	ds_read_b128 v[232:235], v142 offset:0
	ds_read_b128 v[228:231], v138 offset:4096
	ds_read_b128 v[236:239], v142 offset:4096
	s_add_u32 m0, s10, 0x8000
	s_nop 0
	global_load_lds_dwordx4 v200, s[4:5]
	s_add_u32 m0, s10, 0x8400
	s_nop 0
	global_load_lds_dwordx4 v201, s[4:5]
	s_add_u32 m0, s10, 0x8800
	s_nop 0
	global_load_lds_dwordx4 v202, s[4:5]
	s_add_u32 m0, s10, 0x8c00
	s_nop 0
	global_load_lds_dwordx4 v203, s[4:5]
	s_add_u32 s4, s4, 128
	s_addc_u32 s5, s5, 0
	s_mov_b32 s11, 1
; #define G_STORE(S, bf) { *(uint4*)&s->a[bf][srow][skc] = S##a0; *(uint4*)&s->a[bf][srow + 32][skc] = S##a1; \
;     if (MB == 2) { *(uint4*)&s->a[bf][srow + 64][skc] = S##a2; *(uint4*)&s->a[bf][srow + 96][skc] = S##a3; } \
;     *(uint4*)&s->b[bf][srow][skc] = S##b0; *(uint4*)&s->b[bf][srow + 32][skc] = S##b1; *(uint4*)&s->b[bf][srow + 64][skc] = S##b2; *(uint4*)&s->b[bf][srow + 96][skc] = S##b3; }
; template <int MB, bool PF2 = true>
; DI void gemm_main(const u16* __restrict__ A, int lda, const u16* __restrict__ B, int ldb, int K, f32x16 (&acc)[MB][2], GemmLds* s, int tid) {
;     ...
;   for (int kt = 0; kt < KT; kt += 2) {
;     { const int k2 = min((kt + 2) * 64, klast); G_LOAD(q, k2); }
;     __builtin_amdgcn_sched_barrier(0);
;     G_COMPUTE(0);
;     G_STORE(p, 1);
;     __syncthreads();
;     { const int k3 = min((kt + 3) * 64, klast); G_LOAD(p, k3); }
;     __builtin_amdgcn_sched_barrier(0);
;     G_COMPUTE(1);
;     G_STORE(q, 0);
;     __syncthreads();
;   }
.Lmgt_loop:
	ds_read_b128 v[240:243], v139 offset:0
	ds_read_b128 v[192:195], v143 offset:0
	ds_read_b128 v[188:191], v139 offset:4096
	ds_read_b128 v[196:199], v143 offset:4096
	s_waitcnt lgkmcnt(4)
	s_add_u32 m0, s10, 0xc000
	v_mfma_f32_32x32x16_bf16 v[66:81], v[232:235], v[224:227], v[66:81]
	global_load_lds_dwordx4 v130, s[8:9]
	s_add_u32 m0, s10, 0xc400
	v_mfma_f32_32x32x16_bf16 v[82:97], v[236:239], v[224:227], v[82:97]
	global_load_lds_dwordx4 v131, s[8:9]
	s_add_u32 m0, s10, 0xc800
	v_mfma_f32_32x32x16_bf16 v[98:113], v[232:235], v[228:231], v[98:113]
	global_load_lds_dwordx4 v132, s[8:9]
	s_add_u32 m0, s10, 0xcc00
	v_mfma_f32_32x32x16_bf16 v[114:129], v[236:239], v[228:231], v[114:129]
	global_load_lds_dwordx4 v133, s[8:9]
	s_add_u32 s8, s8, 128
	s_addc_u32 s9, s9, 0
	ds_read_b128 v[224:227], v140 offset:0
	ds_read_b128 v[232:235], v144 offset:0
	ds_read_b128 v[228:231], v140 offset:4096
	ds_read_b128 v[236:239], v144 offset:4096
	s_waitcnt lgkmcnt(4)
	v_mfma_f32_32x32x16_bf16 v[66:81], v[192:195], v[240:243], v[66:81]
	v_mfma_f32_32x32x16_bf16 v[82:97], v[196:199], v[240:243], v[82:97]
	v_mfma_f32_32x32x16_bf16 v[98:113], v[192:195], v[188:191], v[98:113]
	v_mfma_f32_32x32x16_bf16 v[114:129], v[196:199], v[188:191], v[114:129]
	ds_read_b128 v[240:243], v141 offset:0
	ds_read_b128 v[192:195], v145 offset:0
	ds_read_b128 v[188:191], v141 offset:4096
	ds_read_b128 v[196:199], v145 offset:4096
	s_waitcnt lgkmcnt(4)
	v_mfma_f32_32x32x16_bf16 v[66:81], v[232:235], v[224:227], v[66:81]
	v_mfma_f32_32x32x16_bf16 v[82:97], v[236:239], v[224:227], v[82:97]
	v_mfma_f32_32x32x16_bf16 v[98:113], v[232:235], v[228:231], v[98:113]
	v_mfma_f32_32x32x16_bf16 v[114:129], v[236:239], v[228:231], v[114:129]
	s_waitcnt vmcnt(0) lgkmcnt(0)
	s_barrier
	ds_read_b128 v[224:227], v138 offset:32768
	ds_read_b128 v[232:235], v142 offset:32768
	ds_read_b128 v[228:231], v138 offset:36864
	ds_read_b128 v[236:239], v142 offset:36864
	s_cmp_eq_u32 s11, 0
	s_cbranch_scc1 .Lmgt_hold0
	s_add_u32 m0, s10, 0x0
	v_mfma_f32_32x32x16_bf16 v[66:81], v[192:195], v[240:243], v[66:81]
	global_load_lds_dwordx4 v200, s[4:5]
	s_add_u32 m0, s10, 0x400
	v_mfma_f32_32x32x16_bf16 v[82:97], v[196:199], v[240:243], v[82:97]
	global_load_lds_dwordx4 v201, s[4:5]
	s_add_u32 m0, s10, 0x800
	v_mfma_f32_32x32x16_bf16 v[98:113], v[192:195], v[188:191], v[98:113]
	global_load_lds_dwordx4 v202, s[4:5]
	s_add_u32 m0, s10, 0xc00
	v_mfma_f32_32x32x16_bf16 v[114:129], v[196:199], v[188:191], v[114:129]
	global_load_lds_dwordx4 v203, s[4:5]
	s_add_u32 s4, s4, 128
	s_addc_u32 s5, s5, 0
	s_branch .Lmgt_held0

; #define G_STORE(S, bf) { *(uint4*)&s->a[bf][srow][skc] = S##a0; *(uint4*)&s->a[bf][srow + 32][skc] = S##a1; \
;     if (MB == 2) { *(uint4*)&s->a[bf][srow + 64][skc] = S##a2; *(uint4*)&s->a[bf][srow + 96][skc] = S##a3; } \
;     *(uint4*)&s->b[bf][srow][skc] = S##b0; *(uint4*)&s->b[bf][srow + 32][skc] = S##b1; *(uint4*)&s->b[bf][srow + 64][skc] = S##b2; *(uint4*)&s->b[bf][srow + 96][skc] = S##b3; }
; template <int MB, bool PF2 = true>
; DI void gemm_main(const u16* __restrict__ A, int lda, const u16* __restrict__ B, int ldb, int K, f32x16 (&acc)[MB][2], GemmLds* s, int tid) {
;     ...
;   for (int kt = 0; kt < KT; kt += 2) {
;     { const int k2 = min((kt + 2) * 64, klast); G_LOAD(q, k2); }
;     __builtin_amdgcn_sched_barrier(0);
;     G_COMPUTE(0);
;     G_STORE(p, 1);
;     __syncthreads();
;     { const int k3 = min((kt + 3) * 64, klast); G_LOAD(p, k3); }
;     __builtin_amdgcn_sched_barrier(0);
;     G_COMPUTE(1);
;     G_STORE(q, 0);
;     __syncthreads();
;   }
.Lmgt_held0:
	s_cmp_eq_u32 s11, 0
	s_cbranch_scc1 .Lmgt_last
	ds_read_b128 v[240:243], v139 offset:32768
	ds_read_b128 v[192:195], v143 offset:32768
	ds_read_b128 v[188:191], v139 offset:36864
	ds_read_b128 v[196:199], v143 offset:36864
	s_waitcnt lgkmcnt(4)
	s_add_u32 m0, s10, 0x4000
	v_mfma_f32_32x32x16_bf16 v[66:81], v[232:235], v[224:227], v[66:81]
	global_load_lds_dwordx4 v130, s[8:9]
	s_add_u32 m0, s10, 0x4400
	v_mfma_f32_32x32x16_bf16 v[82:97], v[236:239], v[224:227], v[82:97]
	global_load_lds_dwordx4 v131, s[8:9]
	s_add_u32 m0, s10, 0x4800
	v_mfma_f32_32x32x16_bf16 v[98:113], v[232:235], v[228:231], v[98:113]
	global_load_lds_dwordx4 v132, s[8:9]
	s_add_u32 m0, s10, 0x4c00
	v_mfma_f32_32x32x16_bf16 v[114:129], v[236:239], v[228:231], v[114:129]
	global_load_lds_dwordx4 v133, s[8:9]
	s_add_u32 s8, s8, 128
	s_addc_u32 s9, s9, 0
	ds_read_b128 v[224:227], v140 offset:32768
	ds_read_b128 v[232:235], v144 offset:32768
	ds_read_b128 v[228:231], v140 offset:36864
	ds_read_b128 v[236:239], v144 offset:36864
	s_waitcnt lgkmcnt(4)
	v_mfma_f32_32x32x16_bf16 v[66:81], v[192:195], v[240:243], v[66:81]
	v_mfma_f32_32x32x16_bf16 v[82:97], v[196:199], v[240:243], v[82:97]
	v_mfma_f32_32x32x16_bf16 v[98:113], v[192:195], v[188:191], v[98:113]
	v_mfma_f32_32x32x16_bf16 v[114:129], v[196:199], v[188:191], v[114:129]
	ds_read_b128 v[240:243], v141 offset:32768
	ds_read_b128 v[192:195], v145 offset:32768
	ds_read_b128 v[188:191], v141 offset:36864
	ds_read_b128 v[196:199], v145 offset:36864
	s_waitcnt lgkmcnt(4)
	v_mfma_f32_32x32x16_bf16 v[66:81], v[232:235], v[224:227], v[66:81]
	v_mfma_f32_32x32x16_bf16 v[82:97], v[236:239], v[224:227], v[82:97]
	v_mfma_f32_32x32x16_bf16 v[98:113], v[232:235], v[228:231], v[98:113]
	v_mfma_f32_32x32x16_bf16 v[114:129], v[236:239], v[228:231], v[114:129]
	s_waitcnt vmcnt(0) lgkmcnt(0)
	s_barrier
	ds_read_b128 v[224:227], v138 offset:0
	ds_read_b128 v[232:235], v142 offset:0
	ds_read_b128 v[228:231], v138 offset:4096
	ds_read_b128 v[236:239], v142 offset:4096
	s_add_u32 m0, s10, 0x8000
	v_mfma_f32_32x32x16_bf16 v[66:81], v[192:195], v[240:243], v[66:81]
	global_load_lds_dwordx4 v200, s[4:5]
	s_add_u32 m0, s10, 0x8400
	v_mfma_f32_32x32x16_bf16 v[82:97], v[196:199], v[240:243], v[82:97]
	global_load_lds_dwordx4 v201, s[4:5]
	s_add_u32 m0, s10, 0x8800
	v_mfma_f32_32x32x16_bf16 v[98:113], v[192:195], v[188:191], v[98:113]
	global_load_lds_dwordx4 v202, s[4:5]
	s_add_u32 m0, s10, 0x8c00
	v_mfma_f32_32x32x16_bf16 v[114:129], v[196:199], v[188:191], v[114:129]
	global_load_lds_dwordx4 v203, s[4:5]
	s_add_u32 s4, s4, 128
	s_addc_u32 s5, s5, 0
	s_sub_u32 s11, s11, 1
	s_branch .Lmgt_loop

; DI float bflo(unsigned v) { return __uint_as_float(v << 16); }
; DI float bfhi(unsigned v) { return __uint_as_float(v & 0xffff0000u); }
; DI void phase_merge(const Params& p, int l, char* smem, int tid) {
;     ...
; #pragma unroll
;       for (int b2 = 0; b2 < 2; b2++)
; #pragma unroll
;         for (int e = 0; e < 8; e++) { accT[0][b2][2 * e] += bflo(sg[b2][e]) * t[0][b2][2 * e]; accT[0][b2][2 * e + 1] += bfhi(sg[b2][e]) * t[0][b2][2 * e + 1]; }
;     }
.Lmgt_nopf:
	ds_read_b128 v[240:243], v139 offset:32768
	ds_read_b128 v[192:195], v143 offset:32768
	ds_read_b128 v[188:191], v139 offset:36864
	ds_read_b128 v[196:199], v143 offset:36864
	s_waitcnt lgkmcnt(4)
	v_mfma_f32_32x32x16_bf16 v[66:81], v[232:235], v[224:227], v[66:81]
	v_mfma_f32_32x32x16_bf16 v[82:97], v[236:239], v[224:227], v[82:97]
	v_mfma_f32_32x32x16_bf16 v[98:113], v[232:235], v[228:231], v[98:113]
	v_mfma_f32_32x32x16_bf16 v[114:129], v[236:239], v[228:231], v[114:129]
	ds_read_b128 v[224:227], v140 offset:32768
	ds_read_b128 v[232:235], v144 offset:32768
	ds_read_b128 v[228:231], v140 offset:36864
	ds_read_b128 v[236:239], v144 offset:36864
	s_waitcnt lgkmcnt(4)
	v_mfma_f32_32x32x16_bf16 v[66:81], v[192:195], v[240:243], v[66:81]
	v_mfma_f32_32x32x16_bf16 v[82:97], v[196:199], v[240:243], v[82:97]
	v_mfma_f32_32x32x16_bf16 v[98:113], v[192:195], v[188:191], v[98:113]
	v_mfma_f32_32x32x16_bf16 v[114:129], v[196:199], v[188:191], v[114:129]
	ds_read_b128 v[240:243], v141 offset:32768
	ds_read_b128 v[192:195], v145 offset:32768
	ds_read_b128 v[188:191], v141 offset:36864
	ds_read_b128 v[196:199], v145 offset:36864
	s_waitcnt lgkmcnt(4)
	v_mfma_f32_32x32x16_bf16 v[66:81], v[232:235], v[224:227], v[66:81]
	v_mfma_f32_32x32x16_bf16 v[82:97], v[236:239], v[224:227], v[82:97]
	v_mfma_f32_32x32x16_bf16 v[98:113], v[232:235], v[228:231], v[98:113]
	v_mfma_f32_32x32x16_bf16 v[114:129], v[236:239], v[228:231], v[114:129]
	s_waitcnt lgkmcnt(0)
	s_barrier
	v_mfma_f32_32x32x16_bf16 v[66:81], v[192:195], v[240:243], v[66:81]
	v_mfma_f32_32x32x16_bf16 v[82:97], v[196:199], v[240:243], v[82:97]
	v_mfma_f32_32x32x16_bf16 v[98:113], v[192:195], v[188:191], v[98:113]
	v_mfma_f32_32x32x16_bf16 v[114:129], v[196:199], v[188:191], v[114:129]
	s_nop 7
	s_nop 7
	v_lshlrev_b32_e32 v147, 16, v156
	v_and_b32_e32 v149, 0xffff0000, v156
	v_fmac_f32_e32 v2, v147, v66
	v_fmac_f32_e32 v3, v149, v67
	v_lshlrev_b32_e32 v151, 16, v157
	v_and_b32_e32 v153, 0xffff0000, v157
	v_fmac_f32_e32 v4, v151, v68
	v_fmac_f32_e32 v5, v153, v69
	v_lshlrev_b32_e32 v147, 16, v158
	v_and_b32_e32 v149, 0xffff0000, v158
	v_fmac_f32_e32 v6, v147, v70
	v_fmac_f32_e32 v7, v149, v71
	v_lshlrev_b32_e32 v151, 16, v159
	v_and_b32_e32 v153, 0xffff0000, v159
	v_fmac_f32_e32 v8, v151, v72
	v_fmac_f32_e32 v9, v153, v73
	v_lshlrev_b32_e32 v147, 16, v160
	v_and_b32_e32 v149, 0xffff0000, v160
	v_fmac_f32_e32 v10, v147, v74
	v_fmac_f32_e32 v11, v149, v75
	v_lshlrev_b32_e32 v151, 16, v161
	v_and_b32_e32 v153, 0xffff0000, v161
	v_fmac_f32_e32 v12, v151, v76
	v_fmac_f32_e32 v13, v153, v77
	v_lshlrev_b32_e32 v147, 16, v162
	v_and_b32_e32 v149, 0xffff0000, v162
	v_fmac_f32_e32 v14, v147, v78
	v_fmac_f32_e32 v15, v149, v79
	v_lshlrev_b32_e32 v151, 16, v163
	v_and_b32_e32 v153, 0xffff0000, v163
	v_fmac_f32_e32 v16, v151, v80
	v_fmac_f32_e32 v17, v153, v81
	v_lshlrev_b32_e32 v147, 16, v164
	v_and_b32_e32 v149, 0xffff0000, v164
	v_fmac_f32_e32 v18, v147, v82
	v_fmac_f32_e32 v19, v149, v83
	v_lshlrev_b32_e32 v151, 16, v165
	v_and_b32_e32 v153, 0xffff0000, v165
	v_fmac_f32_e32 v20, v151, v84
	v_fmac_f32_e32 v21, v153, v85
	v_lshlrev_b32_e32 v147, 16, v166
	v_and_b32_e32 v149, 0xffff0000, v166
	v_fmac_f32_e32 v22, v147, v86
	v_fmac_f32_e32 v23, v149, v87
	v_lshlrev_b32_e32 v151, 16, v167
	v_and_b32_e32 v153, 0xffff0000, v167
	v_fmac_f32_e32 v24, v151, v88
	v_fmac_f32_e32 v25, v153, v89
	v_lshlrev_b32_e32 v147, 16, v168
	v_and_b32_e32 v149, 0xffff0000, v168
	v_fmac_f32_e32 v26, v147, v90
	v_fmac_f32_e32 v27, v149, v91
	v_lshlrev_b32_e32 v151, 16, v169
	v_and_b32_e32 v153, 0xffff0000, v169
	v_fmac_f32_e32 v28, v151, v92
	v_fmac_f32_e32 v29, v153, v93
	v_lshlrev_b32_e32 v147, 16, v170
	v_and_b32_e32 v149, 0xffff0000, v170
	v_fmac_f32_e32 v30, v147, v94
	v_fmac_f32_e32 v31, v149, v95
	v_lshlrev_b32_e32 v151, 16, v171
	v_and_b32_e32 v153, 0xffff0000, v171
	v_fmac_f32_e32 v32, v151, v96
	v_fmac_f32_e32 v33, v153, v97
	v_lshlrev_b32_e32 v147, 16, v172
	v_and_b32_e32 v149, 0xffff0000, v172
	v_fmac_f32_e32 v34, v147, v98
	v_fmac_f32_e32 v35, v149, v99
	v_lshlrev_b32_e32 v151, 16, v173
	v_and_b32_e32 v153, 0xffff0000, v173
	v_fmac_f32_e32 v36, v151, v100
	v_fmac_f32_e32 v37, v153, v101
	v_lshlrev_b32_e32 v147, 16, v174
	v_and_b32_e32 v149, 0xffff0000, v174
	v_fmac_f32_e32 v38, v147, v102
	v_fmac_f32_e32 v39, v149, v103
	v_lshlrev_b32_e32 v151, 16, v175
	v_and_b32_e32 v153, 0xffff0000, v175
	v_fmac_f32_e32 v40, v151, v104
	v_fmac_f32_e32 v41, v153, v105
	v_lshlrev_b32_e32 v147, 16, v176
	v_and_b32_e32 v149, 0xffff0000, v176
	v_fmac_f32_e32 v42, v147, v106
	v_fmac_f32_e32 v43, v149, v107
	v_lshlrev_b32_e32 v151, 16, v177
	v_and_b32_e32 v153, 0xffff0000, v177
	v_fmac_f32_e32 v44, v151, v108
	v_fmac_f32_e32 v45, v153, v109
	v_lshlrev_b32_e32 v147, 16, v178
	v_and_b32_e32 v149, 0xffff0000, v178
	v_fmac_f32_e32 v46, v147, v110
	v_fmac_f32_e32 v47, v149, v111
	v_lshlrev_b32_e32 v151, 16, v179
	v_and_b32_e32 v153, 0xffff0000, v179
	v_fmac_f32_e32 v48, v151, v112
	v_fmac_f32_e32 v49, v153, v113
	v_lshlrev_b32_e32 v147, 16, v180
	v_and_b32_e32 v149, 0xffff0000, v180
	v_fmac_f32_e32 v50, v147, v114
	v_fmac_f32_e32 v51, v149, v115
	v_lshlrev_b32_e32 v151, 16, v181
	v_and_b32_e32 v153, 0xffff0000, v181
	v_fmac_f32_e32 v52, v151, v116
	v_fmac_f32_e32 v53, v153, v117
	v_lshlrev_b32_e32 v147, 16, v182
	v_and_b32_e32 v149, 0xffff0000, v182
	v_fmac_f32_e32 v54, v147, v118
	v_fmac_f32_e32 v55, v149, v119
	v_lshlrev_b32_e32 v151, 16, v183
	v_and_b32_e32 v153, 0xffff0000, v183
	v_fmac_f32_e32 v56, v151, v120
	v_fmac_f32_e32 v57, v153, v121
	v_lshlrev_b32_e32 v147, 16, v184
	v_and_b32_e32 v149, 0xffff0000, v184
	v_fmac_f32_e32 v58, v147, v122
	v_fmac_f32_e32 v59, v149, v123
	v_lshlrev_b32_e32 v151, 16, v185
	v_and_b32_e32 v153, 0xffff0000, v185
	v_fmac_f32_e32 v60, v151, v124
	v_fmac_f32_e32 v61, v153, v125
	v_lshlrev_b32_e32 v147, 16, v186
	v_and_b32_e32 v149, 0xffff0000, v186
	v_fmac_f32_e32 v62, v147, v126
	v_fmac_f32_e32 v63, v149, v127
	v_lshlrev_b32_e32 v151, 16, v187
	v_and_b32_e32 v153, 0xffff0000, v187
	v_fmac_f32_e32 v64, v151, v128
	v_fmac_f32_e32 v65, v153, v129
	s_add_u32 s13, s13, 1
	s_cmp_lt_u32 s13, 8
	s_cbranch_scc1 .Lmg_seg
; DI u16 f2bf(float x) { return (u16)(pack2(x, 0.f) & 0xffffu); }
; DI int crow(int i, int h) { return (i & 3) + 8 * (i >> 2) + 4 * h; }
; DI void phase_merge(const Params& p, int l, char* smem, int tid) {
;     ...
; #pragma unroll
;     for (int nb = 0; nb < 2; nb++) {
;       const int rowb = m0 + wm * 32, col = n0 + wn * 64 + nb * 32 + r;
; #pragma unroll
;       for (int i = 0; i < 16; i++) ACC[(size_t)(rowb + crow(i, h)) * 1024 + col] = f2bf(accT[0][nb][i]);
;     }
	s_sub_u32 s6, s2, s96
	s_subb_u32 s7, s3, s97
	s_add_u32 s6, s6, s90
	s_addc_u32 s7, s7, s91
	s_lshr_b32 s8, s19, 10
	s_add_u32 s6, s6, s8
	s_addc_u32 s7, s7, 0
	v_cvt_pk_bf16_f32 v66, v2, v3
	v_cvt_pk_bf16_f32 v67, v4, v5
	ds_write_b64 v134, v[66:67] offset:0
	v_cvt_pk_bf16_f32 v68, v6, v7
	v_cvt_pk_bf16_f32 v69, v8, v9
	ds_write_b64 v134, v[68:69] offset:16
	v_cvt_pk_bf16_f32 v70, v10, v11
	v_cvt_pk_bf16_f32 v71, v12, v13
	ds_write_b64 v134, v[70:71] offset:32
	v_cvt_pk_bf16_f32 v72, v14, v15
	v_cvt_pk_bf16_f32 v73, v16, v17
	ds_write_b64 v134, v[72:73] offset:48
	v_cvt_pk_bf16_f32 v66, v18, v19
	v_cvt_pk_bf16_f32 v67, v20, v21
	ds_write_b64 v134, v[66:67] offset:64
	v_cvt_pk_bf16_f32 v68, v22, v23
	v_cvt_pk_bf16_f32 v69, v24, v25
	ds_write_b64 v134, v[68:69] offset:80
	v_cvt_pk_bf16_f32 v70, v26, v27
	v_cvt_pk_bf16_f32 v71, v28, v29
	ds_write_b64 v134, v[70:71] offset:96
	v_cvt_pk_bf16_f32 v72, v30, v31
	v_cvt_pk_bf16_f32 v73, v32, v33
	ds_write_b64 v134, v[72:73] offset:112
	v_cvt_pk_bf16_f32 v66, v34, v35
	v_cvt_pk_bf16_f32 v67, v36, v37
	ds_write_b64 v134, v[66:67] offset:4608
	v_cvt_pk_bf16_f32 v68, v38, v39
	v_cvt_pk_bf16_f32 v69, v40, v41
	ds_write_b64 v134, v[68:69] offset:4624
	v_cvt_pk_bf16_f32 v70, v42, v43
	v_cvt_pk_bf16_f32 v71, v44, v45
	ds_write_b64 v134, v[70:71] offset:4640
	v_cvt_pk_bf16_f32 v72, v46, v47
	v_cvt_pk_bf16_f32 v73, v48, v49
	ds_write_b64 v134, v[72:73] offset:4656
	v_cvt_pk_bf16_f32 v66, v50, v51
	v_cvt_pk_bf16_f32 v67, v52, v53
	ds_write_b64 v134, v[66:67] offset:4672
	v_cvt_pk_bf16_f32 v68, v54, v55
	v_cvt_pk_bf16_f32 v69, v56, v57
	ds_write_b64 v134, v[68:69] offset:4688
	v_cvt_pk_bf16_f32 v70, v58, v59
	v_cvt_pk_bf16_f32 v71, v60, v61
	ds_write_b64 v134, v[70:71] offset:4704
	v_cvt_pk_bf16_f32 v72, v62, v63
	v_cvt_pk_bf16_f32 v73, v64, v65
	ds_write_b64 v134, v[72:73] offset:4720
	ds_read_b128 v[74:77], v135 offset:0
	ds_read_b128 v[78:81], v135 offset:1152
	ds_read_b128 v[82:85], v135 offset:2304
	ds_read_b128 v[86:89], v135 offset:3456
	ds_read_b128 v[90:93], v135 offset:4608
	ds_read_b128 v[94:97], v135 offset:5760
	ds_read_b128 v[98:101], v135 offset:6912
	ds_read_b128 v[102:105], v135 offset:8064
	s_waitcnt lgkmcnt(7)
	global_store_dwordx4 v136, v[74:77], s[6:7]
	s_add_u32 s6, s6, 0x4000
	s_addc_u32 s7, s7, 0
	s_waitcnt lgkmcnt(6)
	global_store_dwordx4 v136, v[78:81], s[6:7]
	s_add_u32 s6, s6, 0x4000
	s_addc_u32 s7, s7, 0
	s_waitcnt lgkmcnt(5)
	global_store_dwordx4 v136, v[82:85], s[6:7]
	s_add_u32 s6, s6, 0x4000
	s_addc_u32 s7, s7, 0
	s_waitcnt lgkmcnt(4)
	global_store_dwordx4 v136, v[86:89], s[6:7]
	s_add_u32 s6, s6, 0x4000
	s_addc_u32 s7, s7, 0
	s_waitcnt lgkmcnt(3)
	global_store_dwordx4 v136, v[90:93], s[6:7]
	s_add_u32 s6, s6, 0x4000
	s_addc_u32 s7, s7, 0
	s_waitcnt lgkmcnt(2)
	global_store_dwordx4 v136, v[94:97], s[6:7]
	s_add_u32 s6, s6, 0x4000
	s_addc_u32 s7, s7, 0
	s_waitcnt lgkmcnt(1)
	global_store_dwordx4 v136, v[98:101], s[6:7]
	s_add_u32 s6, s6, 0x4000
	s_addc_u32 s7, s7, 0
	s_waitcnt lgkmcnt(0)
	global_store_dwordx4 v136, v[102:105], s[6:7]
	s_cmp_eq_u32 s18, 0
	s_cbranch_scc1 .Lmg_item
	s_add_u32 s12, s12, s49
	s_branch .Lmg_item

; DI void phase_outproj(const Params& p, int l, char* smem, int tid) {
;   const int lane = tid & 63, w = tid >> 6, r = lane & 31, h = lane >> 5, wm = w >> 1, wn = w & 1;
;   GemmLds* s = (GemmLds*)smem;
;   const u16* ACC = p.Pk;
;   const bool dyn = (l == 0);
;   unsigned* qc = p.bar + 4096 + 384;
;   for (int it = (dyn ? fetch_item(qc, smem) : (int)blockIdx.x); it < 272 * 8; it = (dyn ? fetch_item(qc, smem) : it + (int)gridDim.x)) {
.LBB0_1221:
	s_or_b64 exec, exec, s[4:5]
	v_mov_b32_e32 v0, v206
	s_and_b64 vcc, exec, s[0:1]
	v_mov_b32_e32 v146, s48
	s_waitcnt lgkmcnt(0)
	s_barrier
	v_readlane_b32 s18, v254, 19
	v_and_b32_e32 v112, 63, v206
	v_lshrrev_b32_e32 v113, 6, v206
	v_lshrrev_b32_e32 v114, 3, v112
	v_lshl_add_u32 v114, v113, 5, v114
	v_lshlrev_b32_e32 v114, 11, v114
	v_and_b32_e32 v115, 7, v112
	v_lshrrev_b32_e32 v112, 4, v112
	v_xor_b32_e32 v115, v115, v112
	v_lshl_or_b32 v98, v115, 4, v114
	v_xor_b32_e32 v99, 64, v98
	v_add_u32_e32 v99, 16384, v99
	v_add_u32_e32 v100, 32768, v98
	v_add_u32_e32 v101, 32768, v99
	v_lshrrev_b32_e32 v156, 6, v206
	v_and_b32_e32 v112, 31, v206
	v_bfe_u32 v113, v206, 5, 1
	v_bfe_u32 v114, v112, 1, 3
	v_xor_b32_e32 v114, v114, v113
	v_lshlrev_b32_e32 v114, 4, v114
	v_lshl_or_b32 v114, v112, 7, v114
	v_lshrrev_b32_e32 v115, 7, v206
	v_lshl_add_u32 v102, v115, 13, v114
	v_bfe_u32 v115, v206, 6, 1
	v_lshl_add_u32 v106, v115, 13, v114
	v_add_u32_e32 v106, 0x4000, v106
	v_xor_b32_e32 v103, 32, v102
	v_xor_b32_e32 v107, 32, v106
	v_xor_b32_e32 v104, 64, v102
	v_xor_b32_e32 v108, 64, v106
	v_xor_b32_e32 v105, 96, v102
	v_xor_b32_e32 v109, 96, v106
	v_and_b32_e32 v112, 31, v206
	v_lshrrev_b32_e32 v113, 7, v206
	v_lshl_add_u32 v112, v113, 6, v112
	v_lshlrev_b32_e32 v112, 11, v112
	v_bfe_u32 v113, v206, 6, 1
	v_bfe_u32 v114, v206, 5, 1
	v_lshlrev_b32_e32 v115, 7, v113
	v_lshl_or_b32 v115, v114, 3, v115
	v_or_b32_e32 v110, v112, v115
	v_lshlrev_b32_e32 v111, 8, v113
	v_lshl_or_b32 v111, v114, 4, v111
	v_lshrrev_b32_e32 v112, 6, v206
	v_mul_u32_u24_e32 v112, 0x2400, v112
	v_and_b32_e32 v113, 31, v206
	v_mul_u32_u24_e32 v113, 0x90, v113
	v_bfe_u32 v114, v206, 5, 1
	v_lshl_add_u32 v113, v114, 3, v113
	v_add_u32_e32 v164, v112, v113
	v_bfe_u32 v113, v206, 3, 3
	v_mul_u32_u24_e32 v113, 0x90, v113
	v_and_b32_e32 v114, 7, v206
	v_lshl_add_u32 v113, v114, 4, v113
	v_add_u32_e32 v165, v112, v113
	v_bfe_u32 v112, v206, 3, 3
	v_lshrrev_b32_e32 v113, 7, v206
	v_lshl_add_u32 v112, v113, 6, v112
	v_mul_u32_u24_e32 v112, 0x800, v112
	v_bfe_u32 v113, v206, 6, 1
	v_lshlrev_b32_e32 v113, 7, v113
	v_and_b32_e32 v114, 7, v206
	v_lshl_or_b32 v113, v114, 4, v113
	v_add_u32_e32 v166, v112, v113
	v_readfirstlane_b32 s10, v156
	s_lshl_b32 s10, s10, 12
	s_lshl_b32 s6, s18, 21
	s_add_u32 s14, s96, 0x1cc00000
	s_addc_u32 s15, s97, 0
	s_add_u32 s14, s14, s6
	s_addc_u32 s15, s15, 0
	s_mov_b32 s12, s48

; #define G_STORE(S, bf) { *(uint4*)&s->a[bf][srow][skc] = S##a0; *(uint4*)&s->a[bf][srow + 32][skc] = S##a1; \
;     if (MB == 2) { *(uint4*)&s->a[bf][srow + 64][skc] = S##a2; *(uint4*)&s->a[bf][srow + 96][skc] = S##a3; } \
;     *(uint4*)&s->b[bf][srow][skc] = S##b0; *(uint4*)&s->b[bf][srow + 32][skc] = S##b1; *(uint4*)&s->b[bf][srow + 64][skc] = S##b2; *(uint4*)&s->b[bf][srow + 96][skc] = S##b3; }
; template <int MB, bool PF2 = true>
; DI void gemm_main(const u16* __restrict__ A, int lda, const u16* __restrict__ B, int ldb, int K, f32x16 (&acc)[MB][2], GemmLds* s, int tid) {
;     ...
;   __syncthreads();
;   G_LOAD(p, 0); G_STORE(p, 0);
;   if (!PF2) {
;     __syncthreads();
;     for (int kt = 0; kt < KT; kt++) {
;       const int buf = kt & 1;
;       if (kt + 1 < KT) G_LOAD(p, (kt + 1) * 64);
;       if (buf) { G_COMPUTE(1); } else { G_COMPUTE(0); }
;       if (kt + 1 < KT) { if (buf) { G_STORE(p, 0); } else { G_STORE(p, 1); } }
;       __syncthreads();
;     }
;     return;
;   }
;   const int klast = K - 64;
;   G_LOAD(p, 64);
;   __syncthreads();
; DI void phase_outproj(const Params& p, int l, char* smem, int tid) {
;     ...
;   for (int it = (dyn ? fetch_item(qc, smem) : (int)blockIdx.x); it < 272 * 8; it = (dyn ? fetch_item(qc, smem) : it + (int)gridDim.x)) {
;     const int mt = it >> 3, nt = it & 7, m0 = mt * 128, n0 = nt * 128;
;     if (l == 1 && (mt % 34) < 2) continue;
;     f32x16 acc[2][2]; zero_acc<2>(acc);
;     gemm_main<2>(ACC + (size_t)m0 * 1024, 1024, p.WtOut + (size_t)l * 1024 * 1024 + (size_t)n0 * 1024, 1024, 1024, acc, s, tid);
.Lop_static:
	s_barrier
	s_cmpk_lt_u32 s12, 0x800
	s_cbranch_scc0 .Lop_done
	s_lshr_b32 s6, s12, 8
	s_mul_i32 s7, s6, 34
	s_bfe_u32 s20, s12, 0x50003
	s_add_u32 s20, s20, s7
	s_add_u32 s20, s20, 2
.Lop_decoded:
	s_and_b32 s13, s12, 7
	s_mul_i32 s7, s18, 9
	s_add_u32 s7, s7, s6
	s_mul_i32 s7, s7, 0x3000
	s_lshl_b32 s6, s13, 9
	s_add_u32 s7, s7, s6
	s_add_u32 s7, s7, 0x1d002000
	s_add_u32 s6, s96, s7
	s_addc_u32 s7, s97, 0
	global_load_dwordx4 v[116:119], v111, s[6:7] offset:0
	global_load_dwordx4 v[120:123], v111, s[6:7] offset:32
	global_load_dwordx4 v[124:127], v111, s[6:7] offset:64
	global_load_dwordx4 v[128:131], v111, s[6:7] offset:96
	global_load_dwordx4 v[132:135], v111, s[6:7] offset:128
	global_load_dwordx4 v[136:139], v111, s[6:7] offset:160
	global_load_dwordx4 v[140:143], v111, s[6:7] offset:192
	global_load_dwordx4 v[144:147], v111, s[6:7] offset:224
	s_lshl_b32 s2, s20, 18
	s_add_u32 s4, s90, s2
	s_addc_u32 s5, s91, 0
	s_lshl_b32 s3, s13, 18
	s_add_u32 s8, s14, s3
	s_addc_u32 s9, s15, 0
	s_lshl_b32 s3, s13, 8
	s_add_u32 s2, s2, s3
	s_add_u32 s2, s2, 0x16720000
	s_add_u32 s16, s96, s2
	s_addc_u32 s17, s97, 0
	s_add_u32 s20, s16, 0x10000
	s_addc_u32 s21, s17, 0
	v_mov_b32_e32 v2, 0
	v_mov_b32_e32 v3, 0
	v_mov_b32_e32 v4, 0
	v_mov_b32_e32 v5, 0
	v_mov_b32_e32 v6, 0
	v_mov_b32_e32 v7, 0
	v_mov_b32_e32 v8, 0
	v_mov_b32_e32 v9, 0
	v_mov_b32_e32 v10, 0
	v_mov_b32_e32 v11, 0
	v_mov_b32_e32 v12, 0
	v_mov_b32_e32 v13, 0
	v_mov_b32_e32 v14, 0
	v_mov_b32_e32 v15, 0
	v_mov_b32_e32 v16, 0
	v_mov_b32_e32 v17, 0
	v_mov_b32_e32 v18, 0
	v_mov_b32_e32 v19, 0
	v_mov_b32_e32 v20, 0
	v_mov_b32_e32 v21, 0
	v_mov_b32_e32 v22, 0
	v_mov_b32_e32 v23, 0
	v_mov_b32_e32 v24, 0
	v_mov_b32_e32 v25, 0
	v_mov_b32_e32 v26, 0
	v_mov_b32_e32 v27, 0
	v_mov_b32_e32 v28, 0
	v_mov_b32_e32 v29, 0
	v_mov_b32_e32 v30, 0
	v_mov_b32_e32 v31, 0
	v_mov_b32_e32 v32, 0
	v_mov_b32_e32 v33, 0
	v_mov_b32_e32 v34, 0
	v_mov_b32_e32 v35, 0
	v_mov_b32_e32 v36, 0
	v_mov_b32_e32 v37, 0
	v_mov_b32_e32 v38, 0
	v_mov_b32_e32 v39, 0
	v_mov_b32_e32 v40, 0
	v_mov_b32_e32 v41, 0
	v_mov_b32_e32 v42, 0
	v_mov_b32_e32 v43, 0
	v_mov_b32_e32 v44, 0
	v_mov_b32_e32 v45, 0
	v_mov_b32_e32 v46, 0
	v_mov_b32_e32 v47, 0
	v_mov_b32_e32 v48, 0
	v_mov_b32_e32 v49, 0
	v_mov_b32_e32 v50, 0
	v_mov_b32_e32 v51, 0
	v_mov_b32_e32 v52, 0
	v_mov_b32_e32 v53, 0
	v_mov_b32_e32 v54, 0
	v_mov_b32_e32 v55, 0
	v_mov_b32_e32 v56, 0
	v_mov_b32_e32 v57, 0
	v_mov_b32_e32 v58, 0
	v_mov_b32_e32 v59, 0
	v_mov_b32_e32 v60, 0
	v_mov_b32_e32 v61, 0
	v_mov_b32_e32 v62, 0
	v_mov_b32_e32 v63, 0
	v_mov_b32_e32 v64, 0
	v_mov_b32_e32 v65, 0
	s_add_u32 m0, s10, 0x0
	s_nop 0
	global_load_lds_dwordx4 v98, s[4:5]
	s_add_u32 m0, s10, 0x400
	s_nop 0
	global_load_lds_dwordx4 v99, s[4:5]
	s_add_u32 m0, s10, 0x800
	s_nop 0
	global_load_lds_dwordx4 v100, s[4:5]
	s_add_u32 m0, s10, 0xc00
	s_nop 0
	global_load_lds_dwordx4 v101, s[4:5]
	s_add_u32 m0, s10, 0x4000
	s_nop 0
	global_load_lds_dwordx4 v98, s[8:9]
	s_add_u32 m0, s10, 0x4400
	s_nop 0
	global_load_lds_dwordx4 v99, s[8:9]
	s_add_u32 m0, s10, 0x4800
	s_nop 0
	global_load_lds_dwordx4 v100, s[8:9]
	s_add_u32 m0, s10, 0x4c00
	s_nop 0
	global_load_lds_dwordx4 v101, s[8:9]
	s_add_u32 s4, s4, 128
	s_addc_u32 s5, s5, 0
	s_add_u32 s8, s8, 128
	s_addc_u32 s9, s9, 0
	s_waitcnt vmcnt(0) lgkmcnt(0)
	s_barrier
	ds_read_b128 v[66:69], v102 offset:0
	ds_read_b128 v[74:77], v106 offset:0
	ds_read_b128 v[70:73], v102 offset:4096
	ds_read_b128 v[78:81], v106 offset:4096
	s_add_u32 m0, s10, 0x8000
	s_nop 0
	global_load_lds_dwordx4 v98, s[4:5]
	s_add_u32 m0, s10, 0x8400
	s_nop 0
	global_load_lds_dwordx4 v99, s[4:5]
	s_add_u32 m0, s10, 0x8800
	s_nop 0
	global_load_lds_dwordx4 v100, s[4:5]
	s_add_u32 m0, s10, 0x8c00
	s_nop 0
	global_load_lds_dwordx4 v101, s[4:5]
	s_add_u32 s4, s4, 128
	s_addc_u32 s5, s5, 0
	s_mov_b32 s11, 7

; DI u16 f2bf(float x) { return (u16)(pack2(x, 0.f) & 0xffffu); }
; DI int crow(int i, int h) { return (i & 3) + 8 * (i >> 2) + 4 * h; }
; DI void phase_outproj(const Params& p, int l, char* smem, int tid) {
;     ...
;     u16* O = p.G;
; #pragma unroll
;     for (int mb = 0; mb < 2; mb++)
; #pragma unroll
;       for (int nb = 0; nb < 2; nb++) {
;         const int rowb = m0 + wm * 64 + mb * 32, col = n0 + wn * 64 + nb * 32 + r;
;         const int b = rowb / SEQA, pos0 = rowb % SEQA;
;         const float gate = p.mod[((size_t)l * 9 + ((pos0 < CTXL) ? 8 : b)) * 3072 + 2048 + col];
; #pragma unroll
;         for (int i = 0; i < 16; i++) O[(size_t)(rowb + crow(i, h)) * 1024 + col] = f2bf(gate * acc[mb][nb][i]);
;       }
.Lop_last:
	ds_read_b128 v[82:85], v103 offset:32768
	ds_read_b128 v[90:93], v107 offset:32768
	ds_read_b128 v[86:89], v103 offset:36864
	ds_read_b128 v[94:97], v107 offset:36864
	s_waitcnt lgkmcnt(4)
	v_mfma_f32_32x32x16_bf16 v[2:17], v[74:77], v[66:69], v[2:17]
	v_mfma_f32_32x32x16_bf16 v[18:33], v[78:81], v[66:69], v[18:33]
	v_mfma_f32_32x32x16_bf16 v[34:49], v[74:77], v[70:73], v[34:49]
	v_mfma_f32_32x32x16_bf16 v[50:65], v[78:81], v[70:73], v[50:65]
	ds_read_b128 v[66:69], v104 offset:32768
	ds_read_b128 v[74:77], v108 offset:32768
	ds_read_b128 v[70:73], v104 offset:36864
	ds_read_b128 v[78:81], v108 offset:36864
	s_waitcnt lgkmcnt(4)
	v_mfma_f32_32x32x16_bf16 v[2:17], v[90:93], v[82:85], v[2:17]
	v_mfma_f32_32x32x16_bf16 v[18:33], v[94:97], v[82:85], v[18:33]
	v_mfma_f32_32x32x16_bf16 v[34:49], v[90:93], v[86:89], v[34:49]
	v_mfma_f32_32x32x16_bf16 v[50:65], v[94:97], v[86:89], v[50:65]
	ds_read_b128 v[82:85], v105 offset:32768
	ds_read_b128 v[90:93], v109 offset:32768
	ds_read_b128 v[86:89], v105 offset:36864
	ds_read_b128 v[94:97], v109 offset:36864
	s_waitcnt lgkmcnt(4)
	v_mfma_f32_32x32x16_bf16 v[2:17], v[74:77], v[66:69], v[2:17]
	v_mfma_f32_32x32x16_bf16 v[18:33], v[78:81], v[66:69], v[18:33]
	v_mfma_f32_32x32x16_bf16 v[34:49], v[74:77], v[70:73], v[34:49]
	v_mfma_f32_32x32x16_bf16 v[50:65], v[78:81], v[70:73], v[50:65]
	s_waitcnt vmcnt(0) lgkmcnt(0)
	s_barrier
	v_mfma_f32_32x32x16_bf16 v[2:17], v[90:93], v[82:85], v[2:17]
	v_mfma_f32_32x32x16_bf16 v[18:33], v[94:97], v[82:85], v[18:33]
	v_mfma_f32_32x32x16_bf16 v[34:49], v[90:93], v[86:89], v[34:49]
	v_mfma_f32_32x32x16_bf16 v[50:65], v[94:97], v[86:89], v[50:65]
	s_nop 7
	s_nop 7
	v_mul_f32_e32 v2, v116, v2
	v_mul_f32_e32 v3, v117, v3
	v_mul_f32_e32 v4, v118, v4
	v_mul_f32_e32 v5, v119, v5
	v_mul_f32_e32 v6, v120, v6
	v_mul_f32_e32 v7, v121, v7
	v_mul_f32_e32 v8, v122, v8
	v_mul_f32_e32 v9, v123, v9
	v_mul_f32_e32 v10, v124, v10
	v_mul_f32_e32 v11, v125, v11
	v_mul_f32_e32 v12, v126, v12
	v_mul_f32_e32 v13, v127, v13
	v_mul_f32_e32 v14, v128, v14
	v_mul_f32_e32 v15, v129, v15
	v_mul_f32_e32 v16, v130, v16
	v_mul_f32_e32 v17, v131, v17
	v_mul_f32_e32 v18, v132, v18
	v_mul_f32_e32 v19, v133, v19
	v_mul_f32_e32 v20, v134, v20
	v_mul_f32_e32 v21, v135, v21
	v_mul_f32_e32 v22, v136, v22
	v_mul_f32_e32 v23, v137, v23
	v_mul_f32_e32 v24, v138, v24
	v_mul_f32_e32 v25, v139, v25
	v_mul_f32_e32 v26, v140, v26
	v_mul_f32_e32 v27, v141, v27
	v_mul_f32_e32 v28, v142, v28
	v_mul_f32_e32 v29, v143, v29
	v_mul_f32_e32 v30, v144, v30
	v_mul_f32_e32 v31, v145, v31
	v_mul_f32_e32 v32, v146, v32
	v_mul_f32_e32 v33, v147, v33
	v_mul_f32_e32 v34, v116, v34
	v_mul_f32_e32 v35, v117, v35
	v_mul_f32_e32 v36, v118, v36
	v_mul_f32_e32 v37, v119, v37
	v_mul_f32_e32 v38, v120, v38
	v_mul_f32_e32 v39, v121, v39
	v_mul_f32_e32 v40, v122, v40
	v_mul_f32_e32 v41, v123, v41
	v_mul_f32_e32 v42, v124, v42
	v_mul_f32_e32 v43, v125, v43
	v_mul_f32_e32 v44, v126, v44
	v_mul_f32_e32 v45, v127, v45
	v_mul_f32_e32 v46, v128, v46
	v_mul_f32_e32 v47, v129, v47
	v_mul_f32_e32 v48, v130, v48
	v_mul_f32_e32 v49, v131, v49
	v_mul_f32_e32 v50, v132, v50
	v_mul_f32_e32 v51, v133, v51
	v_mul_f32_e32 v52, v134, v52
	v_mul_f32_e32 v53, v135, v53
	v_mul_f32_e32 v54, v136, v54
	v_mul_f32_e32 v55, v137, v55
	v_mul_f32_e32 v56, v138, v56
	v_mul_f32_e32 v57, v139, v57
	v_mul_f32_e32 v58, v140, v58
	v_mul_f32_e32 v59, v141, v59
	v_mul_f32_e32 v60, v142, v60
	v_mul_f32_e32 v61, v143, v61
	v_mul_f32_e32 v62, v144, v62
	v_mul_f32_e32 v63, v145, v63
	v_mul_f32_e32 v64, v146, v64
	v_mul_f32_e32 v65, v147, v65
	v_cvt_pk_bf16_f32 v156, v2, v3
	v_cvt_pk_bf16_f32 v157, v4, v5
	ds_write_b64 v164, v[156:157] offset:0
	v_cvt_pk_bf16_f32 v158, v6, v7
	v_cvt_pk_bf16_f32 v159, v8, v9
	ds_write_b64 v164, v[158:159] offset:16
	v_cvt_pk_bf16_f32 v160, v10, v11
	v_cvt_pk_bf16_f32 v161, v12, v13
	ds_write_b64 v164, v[160:161] offset:32
	v_cvt_pk_bf16_f32 v162, v14, v15
	v_cvt_pk_bf16_f32 v163, v16, v17
	ds_write_b64 v164, v[162:163] offset:48
	v_cvt_pk_bf16_f32 v156, v18, v19
	v_cvt_pk_bf16_f32 v157, v20, v21
	ds_write_b64 v164, v[156:157] offset:64
	v_cvt_pk_bf16_f32 v158, v22, v23
	v_cvt_pk_bf16_f32 v159, v24, v25
	ds_write_b64 v164, v[158:159] offset:80
	v_cvt_pk_bf16_f32 v160, v26, v27
	v_cvt_pk_bf16_f32 v161, v28, v29
	ds_write_b64 v164, v[160:161] offset:96
	v_cvt_pk_bf16_f32 v162, v30, v31
	v_cvt_pk_bf16_f32 v163, v32, v33
	ds_write_b64 v164, v[162:163] offset:112
	v_cvt_pk_bf16_f32 v156, v34, v35
	v_cvt_pk_bf16_f32 v157, v36, v37
	ds_write_b64 v164, v[156:157] offset:4608
	v_cvt_pk_bf16_f32 v158, v38, v39
	v_cvt_pk_bf16_f32 v159, v40, v41
	ds_write_b64 v164, v[158:159] offset:4624
	v_cvt_pk_bf16_f32 v160, v42, v43
	v_cvt_pk_bf16_f32 v161, v44, v45
	ds_write_b64 v164, v[160:161] offset:4640
	v_cvt_pk_bf16_f32 v162, v46, v47
	v_cvt_pk_bf16_f32 v163, v48, v49
	ds_write_b64 v164, v[162:163] offset:4656
	v_cvt_pk_bf16_f32 v156, v50, v51
	v_cvt_pk_bf16_f32 v157, v52, v53
	ds_write_b64 v164, v[156:157] offset:4672
	v_cvt_pk_bf16_f32 v158, v54, v55
	v_cvt_pk_bf16_f32 v159, v56, v57
	ds_write_b64 v164, v[158:159] offset:4688
	v_cvt_pk_bf16_f32 v160, v58, v59
	v_cvt_pk_bf16_f32 v161, v60, v61
	ds_write_b64 v164, v[160:161] offset:4704
	v_cvt_pk_bf16_f32 v162, v62, v63
	v_cvt_pk_bf16_f32 v163, v64, v65
	ds_write_b64 v164, v[162:163] offset:4720
	ds_read_b128 v[66:69], v165 offset:0
	ds_read_b128 v[70:73], v165 offset:1152
	ds_read_b128 v[74:77], v165 offset:2304
	ds_read_b128 v[78:81], v165 offset:3456
	ds_read_b128 v[82:85], v165 offset:4608
	ds_read_b128 v[86:89], v165 offset:5760
	ds_read_b128 v[90:93], v165 offset:6912
	ds_read_b128 v[94:97], v165 offset:8064
	s_waitcnt lgkmcnt(7)
	global_store_dwordx4 v166, v[66:69], s[16:17]
	s_add_u32 s16, s16, 0x4000
	s_addc_u32 s17, s17, 0
	s_waitcnt lgkmcnt(6)
	global_store_dwordx4 v166, v[70:73], s[16:17]
	s_add_u32 s16, s16, 0x4000
	s_addc_u32 s17, s17, 0
	s_waitcnt lgkmcnt(5)
	global_store_dwordx4 v166, v[74:77], s[16:17]
	s_add_u32 s16, s16, 0x4000
	s_addc_u32 s17, s17, 0
	s_waitcnt lgkmcnt(4)
	global_store_dwordx4 v166, v[78:81], s[16:17]
	s_add_u32 s16, s16, 0x4000
	s_addc_u32 s17, s17, 0
	s_waitcnt lgkmcnt(3)
	global_store_dwordx4 v166, v[82:85], s[16:17]
	s_add_u32 s16, s16, 0x4000
	s_addc_u32 s17, s17, 0
	s_waitcnt lgkmcnt(2)
	global_store_dwordx4 v166, v[86:89], s[16:17]
	s_add_u32 s16, s16, 0x4000
	s_addc_u32 s17, s17, 0
	s_waitcnt lgkmcnt(1)
	global_store_dwordx4 v166, v[90:93], s[16:17]
	s_add_u32 s16, s16, 0x4000
	s_addc_u32 s17, s17, 0
	s_waitcnt lgkmcnt(0)
	global_store_dwordx4 v166, v[94:97], s[16:17]
	s_cmp_eq_u32 s18, 0
	s_cbranch_scc1 .Lop_item
	s_add_u32 s12, s12, s49
	s_branch .Lop_item
